# LRU GEMM epilogue: the eight u-row loads of each half issued up front, handed over with counted vmcnt (no per-step global round trip or store-ack wait)
# speedup vs baseline: 1.0035x; 1.0001x over previous
.LBB0_312:
	s_or_b64 exec, exec, s[2:3]
	v_add_f32_e32 v5, v5, v69
	v_add_f32_e32 v2, v2, v66
	v_add_f32_e32 v3, v3, v67
	v_add_f32_e32 v4, v4, v68
	v_mul_f32_e32 v5, 0xbfb8aa3b, v5
	v_mul_f32_e32 v2, 0xbfb8aa3b, v2
	v_mul_f32_e32 v3, 0xbfb8aa3b, v3
	v_mul_f32_e32 v4, 0xbfb8aa3b, v4
	v_exp_f32_e32 v5, v5
	v_exp_f32_e32 v2, v2
	v_exp_f32_e32 v3, v3
	v_exp_f32_e32 v4, v4
	v_mul_f32_e32 v13, 0x3fb8aa3b, v13
	v_exp_f32_e32 v16, v13
	v_mul_f32_e32 v13, 0x3fb8aa3b, v14
	v_add_f32_e32 v5, 1.0, v5
	v_add_f32_e32 v2, 1.0, v2
	v_add_f32_e32 v3, 1.0, v3
	v_add_f32_e32 v4, 1.0, v4
	v_exp_f32_e32 v17, v13
	v_mul_f32_e32 v13, 0x3fb8aa3b, v15
	v_mul_f32_e32 v9, 0x3fb8aa3b, v9
	v_rcp_f32_e32 v5, v5
	v_rcp_f32_e32 v2, v2
	v_sqrt_f32_e32 v14, v6
	v_rcp_f32_e32 v3, v3
	v_sqrt_f32_e32 v15, v12
	v_rcp_f32_e32 v4, v4
	v_sqrt_f32_e32 v6, v7
	v_sqrt_f32_e32 v7, v8
	v_exp_f32_e32 v18, v13
	v_exp_f32_e32 v19, v9
	v_pk_mul_f32 v[2:3], v[2:3], v[14:15]
	s_nop 0
	v_lshlrev_b32_e32 v12, 16, v10
	v_and_b32_e32 v13, 0xffff0000, v10
	v_lshlrev_b32_e32 v8, 16, v11
	v_and_b32_e32 v9, 0xffff0000, v11
	v_pk_mul_f32 v[4:5], v[4:5], v[6:7]
	s_and_b64 vcc, exec, s[6:7]
	s_mov_b32 s30, s16
	s_mov_b32 s2, s18
	s_mov_b64 s[34:35], s[28:29]
	s_mov_b64 s[36:37], s[26:27]
	v_pk_mul_f32 v[2:3], v[2:3], v[12:13]
	v_pk_mul_f32 v[4:5], v[4:5], v[8:9]
	global_store_dwordx4 v[78:79], v[16:19], off offset:64
	global_store_dwordx4 v[80:81], v[2:5], off offset:64
	s_cbranch_vccnz .LBB0_589

.LBB0_325:
	s_or_b64 exec, exec, s[8:9]
	v_lshl_add_u32 v140, s2, 8, v188
	v_ashrrev_i32_e32 v141, 31, v140
	v_readlane_b32 s0, v255, 17
	v_lshlrev_b64 v[138:139], 10, v[140:141]
	v_readlane_b32 s1, v255, 18
	v_add_f32_e32 v134, v134, v98
	v_mul_f32_e32 v134, 0xbfb8aa3b, v134
	v_lshl_add_u64 v[138:139], s[0:1], 0, v[138:139]
	v_lshl_add_u64 v[138:139], v[168:169], 1, v[138:139]
	global_load_dwordx2 v[170:171], v[138:139], off
	s_mov_b32 s99, 0
	s_mov_b32 s98, 0x4000
	v_lshl_add_u64 v[242:243], s[98:99], 0, v[138:139]
	global_load_dwordx2 v[242:243], v[242:243], off
	s_mov_b32 s98, 0x8000
	v_lshl_add_u64 v[244:245], s[98:99], 0, v[138:139]
	global_load_dwordx2 v[244:245], v[244:245], off
	s_mov_b32 s98, 0xc000
	v_lshl_add_u64 v[246:247], s[98:99], 0, v[138:139]
	global_load_dwordx2 v[246:247], v[246:247], off
	s_mov_b32 s98, 0x20000
	v_lshl_add_u64 v[248:249], s[98:99], 0, v[138:139]
	global_load_dwordx2 v[248:249], v[248:249], off
	s_mov_b32 s98, 0x24000
	v_lshl_add_u64 v[250:251], s[98:99], 0, v[138:139]
	global_load_dwordx2 v[250:251], v[250:251], off
	s_mov_b32 s98, 0x28000
	v_lshl_add_u64 v[180:181], s[98:99], 0, v[138:139]
	global_load_dwordx2 v[180:181], v[180:181], off
	s_mov_b32 s98, 0x2c000
	v_lshl_add_u64 v[182:183], s[98:99], 0, v[138:139]
	global_load_dwordx2 v[182:183], v[182:183], off
	v_exp_f32_e32 v134, v134
	v_mul_f32_e32 v153, 0xc1000000, v192
	s_mov_b32 s0, 0xbe800000
	v_add_f32_e32 v134, 1.0, v134
	v_rcp_f32_e32 v134, v134
	s_nop 0
	v_mul_f32_e32 v134, v134, v153
	v_add_f32_e32 v192, v134, v134
	v_cmp_nlt_f32_e32 vcc, s0, v192
	s_and_saveexec_b64 s[2:3], vcc
	s_xor_b64 s[2:3], exec, s[2:3]
	v_mul_f32_e32 v144, 0x3fb8aa3b, v192
	v_exp_f32_e32 v144, v144
	s_nop 0
	v_sub_f32_e32 v195, 1.0, v144
	s_andn2_saveexec_b64 s[2:3], s[2:3]
	v_fmamk_f32 v144, v192, 0x3c088889, v174
	v_fmaak_f32 v144, v192, v144, 0x3e2aaaab
	v_fma_f32 v144, v192, v144, 0.5
	v_fma_f32 v144, v192, v144, 1.0
	v_mul_f32_e64 v195, v144, -v192
	s_or_b64 exec, exec, s[2:3]
	v_add_f32_e32 v135, v135, v99
	v_mul_f32_e32 v135, 0xbfb8aa3b, v135
	v_exp_f32_e32 v135, v135
	v_mul_f32_e32 v192, 0xc1000000, v193
	v_add_f32_e32 v135, 1.0, v135
	v_rcp_f32_e32 v135, v135
	s_nop 0
	v_mul_f32_e32 v135, v135, v192
	v_add_f32_e32 v193, v135, v135
	v_cmp_nlt_f32_e32 vcc, s0, v193
	s_and_saveexec_b64 s[2:3], vcc
	s_xor_b64 s[2:3], exec, s[2:3]
	v_mul_f32_e32 v144, 0x3fb8aa3b, v193
	v_exp_f32_e32 v144, v144
	s_nop 0
	v_sub_f32_e32 v197, 1.0, v144
	s_andn2_saveexec_b64 s[2:3], s[2:3]
	v_fmamk_f32 v144, v193, 0x3c088889, v174
	v_fmaak_f32 v144, v193, v144, 0x3e2aaaab
	v_fma_f32 v144, v193, v144, 0.5
	v_fma_f32 v144, v193, v144, 1.0
	v_mul_f32_e64 v197, v144, -v193
	s_or_b64 exec, exec, s[2:3]
	v_add_f32_e32 v136, v136, v100
	v_mul_f32_e32 v136, 0xbfb8aa3b, v136
	v_exp_f32_e32 v136, v136
	v_mul_f32_e32 v193, 0xc1000000, v194
	v_add_f32_e32 v136, 1.0, v136
	v_rcp_f32_e32 v136, v136
	s_nop 0
	v_mul_f32_e32 v136, v136, v193
	v_add_f32_e32 v194, v136, v136
	v_cmp_nlt_f32_e32 vcc, s0, v194
	s_and_saveexec_b64 s[2:3], vcc
	s_xor_b64 s[2:3], exec, s[2:3]
	v_mul_f32_e32 v144, 0x3fb8aa3b, v194
	v_exp_f32_e32 v144, v144
	s_nop 0
	v_sub_f32_e32 v198, 1.0, v144
	s_andn2_saveexec_b64 s[2:3], s[2:3]
	v_fmamk_f32 v144, v194, 0x3c088889, v174
	v_fmaak_f32 v144, v194, v144, 0x3e2aaaab
	v_fma_f32 v144, v194, v144, 0.5
	v_fma_f32 v144, v194, v144, 1.0
	v_mul_f32_e64 v198, v144, -v194
	s_or_b64 exec, exec, s[2:3]
	v_add_f32_e32 v137, v137, v101
	v_mul_f32_e32 v137, 0xbfb8aa3b, v137
	v_exp_f32_e32 v137, v137
	v_mul_f32_e32 v194, 0xc1000000, v196
	v_add_f32_e32 v137, 1.0, v137
	v_rcp_f32_e32 v137, v137
	s_nop 0
	v_mul_f32_e32 v137, v137, v194
	v_add_f32_e32 v199, v137, v137
	v_cmp_nlt_f32_e32 vcc, s0, v199
	s_and_saveexec_b64 s[2:3], vcc
	s_xor_b64 s[2:3], exec, s[2:3]
	v_mul_f32_e32 v144, 0x3fb8aa3b, v199
	v_exp_f32_e32 v144, v144
	s_nop 0
	v_sub_f32_e32 v196, 1.0, v144
	s_andn2_saveexec_b64 s[2:3], s[2:3]
	v_fmamk_f32 v144, v199, 0x3c088889, v174
	v_fmaak_f32 v144, v199, v144, 0x3e2aaaab
	v_fma_f32 v144, v199, v144, 0.5
	v_fma_f32 v144, v199, v144, 1.0
	v_mul_f32_e64 v196, v144, -v199
	s_or_b64 exec, exec, s[2:3]
	v_add_f32_e32 v130, v130, v94
	v_mul_f32_e32 v130, 0xbfb8aa3b, v130
	v_exp_f32_e32 v130, v130
	v_sqrt_f32_e32 v144, v195
	v_add_f32_e32 v131, v131, v95
	v_lshlrev_b64 v[204:205], 9, v[140:141]
	v_add_f32_e32 v130, 1.0, v130
	v_and_b32_e32 v141, 0x7cf, v140
	v_rcp_f32_e32 v130, v130
	v_mul_f32_e32 v131, 0xbfb8aa3b, v131
	v_cmp_gt_i32_e32 vcc, s33, v140
	v_cmp_eq_u32_e64 s[8:9], 0, v141
	v_exp_f32_e32 v131, v131
	s_and_b64 s[2:3], vcc, s[8:9]
	v_cndmask_b32_e64 v144, v144, 1.0, s[2:3]
	s_waitcnt vmcnt(7)
	v_lshlrev_b32_e32 v141, 16, v170
	v_mul_f32_e32 v130, v130, v144
	v_mul_f32_e32 v200, v130, v141
	v_add_f32_e32 v130, 1.0, v131
	v_sqrt_f32_e32 v141, v197
	v_add_f32_e32 v132, v132, v96
	v_rcp_f32_e32 v130, v130
	v_mul_f32_e32 v132, 0xbfb8aa3b, v132
	v_exp_f32_e32 v132, v132
	v_mul_f32_e32 v131, 0x3fb8aa3b, v135
	v_cndmask_b32_e64 v141, v141, 1.0, s[2:3]
	v_exp_f32_e32 v135, v131
	v_and_b32_e32 v131, 0xffff0000, v170
	v_mul_f32_e32 v130, v130, v141
	v_mul_f32_e32 v201, v130, v131
	v_add_f32_e32 v130, 1.0, v132
	v_sqrt_f32_e32 v132, v198
	v_add_f32_e32 v133, v133, v97
	v_rcp_f32_e32 v130, v130
	v_mul_f32_e32 v133, 0xbfb8aa3b, v133
	v_exp_f32_e32 v133, v133
	v_mul_f32_e32 v131, 0x3fb8aa3b, v136
	v_cndmask_b32_e64 v132, v132, 1.0, s[2:3]
	v_exp_f32_e32 v136, v131
	v_lshlrev_b32_e32 v131, 16, v171
	v_mul_f32_e32 v130, v130, v132
	v_mul_f32_e32 v202, v130, v131
	v_add_f32_e32 v130, 1.0, v133
	v_sqrt_f32_e32 v131, v196
	v_rcp_f32_e32 v130, v130
	v_mul_f32_e32 v134, 0x3fb8aa3b, v134
	v_mul_f32_e32 v132, 0x3fb8aa3b, v137
	v_cndmask_b32_e64 v131, v131, 1.0, s[2:3]
	v_exp_f32_e32 v134, v134
	v_exp_f32_e32 v137, v132
	v_and_b32_e32 v132, 0xffff0000, v171
	v_mul_f32_e32 v130, v130, v131
	v_mul_f32_e32 v203, v130, v132
	v_lshlrev_b64 v[132:133], 2, v[204:205]
	v_lshl_add_u64 v[130:131], s[20:21], 0, v[132:133]
	v_or_b32_e32 v170, 16, v140
	v_lshl_add_u64 v[130:131], v[130:131], 0, v[166:167]
	v_ashrrev_i32_e32 v171, 31, v170
	v_readlane_b32 s0, v255, 17
	global_store_dwordx4 v[130:131], v[134:137], off
	v_lshl_add_u64 v[132:133], s[22:23], 0, v[132:133]
	v_readlane_b32 s1, v255, 18
	v_lshlrev_b64 v[134:135], 10, v[170:171]
	v_lshl_add_u64 v[132:133], v[132:133], 0, v[166:167]
	v_lshl_add_u64 v[134:135], s[0:1], 0, v[134:135]
	global_store_dwordx4 v[132:133], v[200:203], off
	v_lshl_add_u64 v[134:135], v[168:169], 1, v[134:135]
	s_waitcnt vmcnt(8)
	s_nop 1
	v_mov_b32_e32 v136, v242
	v_mov_b32_e32 v137, v243
	v_add_f32_e32 v126, v126, v98
	v_mul_f32_e32 v126, 0xbfb8aa3b, v126
	v_exp_f32_e32 v126, v126
	s_mov_b32 s0, 0xbe800000
	v_add_f32_e32 v126, 1.0, v126
	v_rcp_f32_e32 v126, v126
	s_nop 0
	v_mul_f32_e32 v126, v126, v153
	v_add_f32_e32 v195, v126, v126
	v_cmp_nlt_f32_e32 vcc, s0, v195
	s_and_saveexec_b64 s[4:5], vcc
	s_xor_b64 s[8:9], exec, s[4:5]
	v_mul_f32_e32 v141, 0x3fb8aa3b, v195
	v_exp_f32_e32 v141, v141
	s_nop 0
	v_sub_f32_e32 v141, 1.0, v141
	s_andn2_saveexec_b64 s[8:9], s[8:9]
	v_fmamk_f32 v141, v195, 0x3c088889, v174
	v_fmaak_f32 v141, v195, v141, 0x3e2aaaab
	v_fma_f32 v141, v195, v141, 0.5
	v_fma_f32 v141, v195, v141, 1.0
	v_mul_f32_e64 v141, v141, -v195
	s_or_b64 exec, exec, s[8:9]
	v_add_f32_e32 v127, v127, v99
	v_mul_f32_e32 v127, 0xbfb8aa3b, v127
	v_exp_f32_e32 v127, v127
	s_nop 0
	v_add_f32_e32 v127, 1.0, v127
	v_rcp_f32_e32 v127, v127
	s_nop 0
	v_mul_f32_e32 v127, v127, v192
	v_add_f32_e32 v196, v127, v127
	v_cmp_nlt_f32_e32 vcc, s0, v196
	s_and_saveexec_b64 s[4:5], vcc
	s_xor_b64 s[8:9], exec, s[4:5]
	v_mul_f32_e32 v144, 0x3fb8aa3b, v196
	v_exp_f32_e32 v144, v144
	s_nop 0
	v_sub_f32_e32 v195, 1.0, v144
	s_andn2_saveexec_b64 s[8:9], s[8:9]
	v_fmamk_f32 v144, v196, 0x3c088889, v174
	v_fmaak_f32 v144, v196, v144, 0x3e2aaaab
	v_fma_f32 v144, v196, v144, 0.5
	v_fma_f32 v144, v196, v144, 1.0
	v_mul_f32_e64 v195, v144, -v196
	s_or_b64 exec, exec, s[8:9]
	v_add_f32_e32 v128, v128, v100
	v_mul_f32_e32 v128, 0xbfb8aa3b, v128
	v_exp_f32_e32 v128, v128
	s_nop 0
	v_add_f32_e32 v128, 1.0, v128
	v_rcp_f32_e32 v128, v128
	s_nop 0
	v_mul_f32_e32 v128, v128, v193
	v_add_f32_e32 v197, v128, v128
	v_cmp_nlt_f32_e32 vcc, s0, v197
	s_and_saveexec_b64 s[4:5], vcc
	s_xor_b64 s[8:9], exec, s[4:5]
	v_mul_f32_e32 v144, 0x3fb8aa3b, v197
	v_exp_f32_e32 v144, v144
	s_nop 0
	v_sub_f32_e32 v196, 1.0, v144
	s_andn2_saveexec_b64 s[8:9], s[8:9]
	v_fmamk_f32 v144, v197, 0x3c088889, v174
	v_fmaak_f32 v144, v197, v144, 0x3e2aaaab
	v_fma_f32 v144, v197, v144, 0.5
	v_fma_f32 v144, v197, v144, 1.0
	v_mul_f32_e64 v196, v144, -v197
	s_or_b64 exec, exec, s[8:9]
	v_add_f32_e32 v129, v129, v101
	v_mul_f32_e32 v129, 0xbfb8aa3b, v129
	v_exp_f32_e32 v129, v129
	s_nop 0
	v_add_f32_e32 v129, 1.0, v129
	v_rcp_f32_e32 v129, v129
	s_nop 0
	v_mul_f32_e32 v129, v129, v194
	v_add_f32_e32 v198, v129, v129
	v_cmp_nlt_f32_e32 vcc, s0, v198
	s_and_saveexec_b64 s[4:5], vcc
	s_xor_b64 s[8:9], exec, s[4:5]
	v_mul_f32_e32 v144, 0x3fb8aa3b, v198
	v_exp_f32_e32 v144, v144
	s_nop 0
	v_sub_f32_e32 v197, 1.0, v144
	s_andn2_saveexec_b64 s[8:9], s[8:9]
	v_fmamk_f32 v144, v198, 0x3c088889, v174
	v_fmaak_f32 v144, v198, v144, 0x3e2aaaab
	v_fma_f32 v144, v198, v144, 0.5
	v_fma_f32 v144, v198, v144, 1.0
	v_mul_f32_e64 v197, v144, -v198
	s_or_b64 exec, exec, s[8:9]
	v_add_f32_e32 v122, v122, v94
	v_mul_f32_e32 v122, 0xbfb8aa3b, v122
	v_exp_f32_e32 v122, v122
	v_add_f32_e32 v123, v123, v95
	v_sqrt_f32_e32 v141, v141
	v_mul_f32_e32 v123, 0xbfb8aa3b, v123
	v_add_f32_e32 v122, 1.0, v122
	v_rcp_f32_e32 v122, v122
	v_exp_f32_e32 v123, v123
	s_nop 0
	v_lshlrev_b32_e32 v144, 16, v136
	v_add_f32_e32 v124, v124, v96
	v_mul_f32_e32 v122, v122, v141
	v_mul_f32_e32 v198, v122, v144
	v_add_f32_e32 v122, 1.0, v123
	v_mul_f32_e32 v123, 0x3fb8aa3b, v127
	v_rcp_f32_e32 v122, v122
	v_exp_f32_e32 v127, v123
	v_sqrt_f32_e32 v123, v195
	v_mul_f32_e32 v124, 0xbfb8aa3b, v124
	v_exp_f32_e32 v124, v124
	v_and_b32_e32 v136, 0xffff0000, v136
	v_mul_f32_e32 v122, v122, v123
	v_mul_f32_e32 v199, v122, v136
	v_add_f32_e32 v122, 1.0, v124
	v_mul_f32_e32 v123, 0x3fb8aa3b, v128
	v_add_f32_e32 v124, v125, v97
	v_rcp_f32_e32 v122, v122
	v_exp_f32_e32 v128, v123
	v_sqrt_f32_e32 v123, v196
	v_mul_f32_e32 v124, 0xbfb8aa3b, v124
	v_exp_f32_e32 v124, v124
	v_lshlrev_b32_e32 v125, 16, v137
	v_mul_f32_e32 v122, v122, v123
	v_mul_f32_e32 v200, v122, v125
	v_add_f32_e32 v122, 1.0, v124
	v_rcp_f32_e32 v122, v122
	v_sqrt_f32_e32 v123, v197
	v_mul_f32_e32 v126, 0x3fb8aa3b, v126
	v_mul_f32_e32 v124, 0x3fb8aa3b, v129
	v_lshlrev_b64 v[170:171], 9, v[170:171]
	v_exp_f32_e32 v126, v126
	v_exp_f32_e32 v129, v124
	v_and_b32_e32 v124, 0xffff0000, v137
	v_mul_f32_e32 v122, v122, v123
	v_mul_f32_e32 v201, v122, v124
	v_lshlrev_b64 v[124:125], 2, v[170:171]
	v_lshl_add_u64 v[122:123], s[20:21], 0, v[124:125]
	v_or_b32_e32 v136, 32, v140
	v_lshl_add_u64 v[122:123], v[122:123], 0, v[166:167]
	v_ashrrev_i32_e32 v137, 31, v136
	v_readlane_b32 s0, v255, 17
	global_store_dwordx4 v[122:123], v[126:129], off
	v_lshl_add_u64 v[124:125], s[22:23], 0, v[124:125]
	v_readlane_b32 s1, v255, 18
	v_lshlrev_b64 v[126:127], 10, v[136:137]
	v_lshl_add_u64 v[124:125], v[124:125], 0, v[166:167]
	v_lshl_add_u64 v[126:127], s[0:1], 0, v[126:127]
	global_store_dwordx4 v[124:125], v[198:201], off
	v_lshl_add_u64 v[126:127], v[168:169], 1, v[126:127]
	s_waitcnt vmcnt(9)
	s_nop 1
	v_mov_b32_e32 v128, v244
	v_mov_b32_e32 v129, v245
	v_add_f32_e32 v118, v118, v98
	v_mul_f32_e32 v118, 0xbfb8aa3b, v118
	v_exp_f32_e32 v118, v118
	s_mov_b32 s0, 0xbe800000
	v_add_f32_e32 v118, 1.0, v118
	v_rcp_f32_e32 v118, v118
	s_nop 0
	v_mul_f32_e32 v118, v118, v153
	v_add_f32_e32 v170, v118, v118
	v_cmp_nlt_f32_e32 vcc, s0, v170
	s_and_saveexec_b64 s[4:5], vcc
	s_xor_b64 s[8:9], exec, s[4:5]
	v_mul_f32_e32 v141, 0x3fb8aa3b, v170
	v_exp_f32_e32 v141, v141
	s_nop 0
	v_sub_f32_e32 v141, 1.0, v141
	s_andn2_saveexec_b64 s[8:9], s[8:9]
	v_fmamk_f32 v141, v170, 0x3c088889, v174
	v_fmaak_f32 v141, v170, v141, 0x3e2aaaab
	v_fma_f32 v141, v170, v141, 0.5
	v_fma_f32 v141, v170, v141, 1.0
	v_mul_f32_e64 v141, v141, -v170
	s_or_b64 exec, exec, s[8:9]
	v_add_f32_e32 v119, v119, v99
	v_mul_f32_e32 v119, 0xbfb8aa3b, v119
	v_exp_f32_e32 v119, v119
	s_nop 0
	v_add_f32_e32 v119, 1.0, v119
	v_rcp_f32_e32 v119, v119
	s_nop 0
	v_mul_f32_e32 v119, v119, v192
	v_add_f32_e32 v171, v119, v119
	v_cmp_nlt_f32_e32 vcc, s0, v171
	s_and_saveexec_b64 s[4:5], vcc
	s_xor_b64 s[8:9], exec, s[4:5]
	v_mul_f32_e32 v144, 0x3fb8aa3b, v171
	v_exp_f32_e32 v144, v144
	s_nop 0
	v_sub_f32_e32 v170, 1.0, v144
	s_andn2_saveexec_b64 s[8:9], s[8:9]
	v_fmamk_f32 v144, v171, 0x3c088889, v174
	v_fmaak_f32 v144, v171, v144, 0x3e2aaaab
	v_fma_f32 v144, v171, v144, 0.5
	v_fma_f32 v144, v171, v144, 1.0
	v_mul_f32_e64 v170, v144, -v171
	s_or_b64 exec, exec, s[8:9]
	v_add_f32_e32 v120, v120, v100
	v_mul_f32_e32 v120, 0xbfb8aa3b, v120
	v_exp_f32_e32 v120, v120
	s_nop 0
	v_add_f32_e32 v120, 1.0, v120
	v_rcp_f32_e32 v120, v120
	s_nop 0
	v_mul_f32_e32 v120, v120, v193
	v_add_f32_e32 v195, v120, v120
	v_cmp_nlt_f32_e32 vcc, s0, v195
	s_and_saveexec_b64 s[4:5], vcc
	s_xor_b64 s[8:9], exec, s[4:5]
	v_mul_f32_e32 v144, 0x3fb8aa3b, v195
	v_exp_f32_e32 v144, v144
	s_nop 0
	v_sub_f32_e32 v171, 1.0, v144
	s_andn2_saveexec_b64 s[8:9], s[8:9]
	v_fmamk_f32 v144, v195, 0x3c088889, v174
	v_fmaak_f32 v144, v195, v144, 0x3e2aaaab
	v_fma_f32 v144, v195, v144, 0.5
	v_fma_f32 v144, v195, v144, 1.0
	v_mul_f32_e64 v171, v144, -v195
	s_or_b64 exec, exec, s[8:9]
	v_add_f32_e32 v121, v121, v101
	v_mul_f32_e32 v121, 0xbfb8aa3b, v121
	v_exp_f32_e32 v121, v121
	s_nop 0
	v_add_f32_e32 v121, 1.0, v121
	v_rcp_f32_e32 v121, v121
	s_nop 0
	v_mul_f32_e32 v121, v121, v194
	v_add_f32_e32 v196, v121, v121
	v_cmp_nlt_f32_e32 vcc, s0, v196
	s_and_saveexec_b64 s[4:5], vcc
	s_xor_b64 s[8:9], exec, s[4:5]
	v_mul_f32_e32 v144, 0x3fb8aa3b, v196
	v_exp_f32_e32 v144, v144
	s_nop 0
	v_sub_f32_e32 v195, 1.0, v144
	s_andn2_saveexec_b64 s[8:9], s[8:9]
	v_fmamk_f32 v144, v196, 0x3c088889, v174
	v_fmaak_f32 v144, v196, v144, 0x3e2aaaab
	v_fma_f32 v144, v196, v144, 0.5
	v_fma_f32 v144, v196, v144, 1.0
	v_mul_f32_e64 v195, v144, -v196
	s_or_b64 exec, exec, s[8:9]
	v_add_f32_e32 v114, v114, v94
	v_mul_f32_e32 v114, 0xbfb8aa3b, v114
	v_exp_f32_e32 v114, v114
	v_add_f32_e32 v115, v115, v95
	v_sqrt_f32_e32 v141, v141
	v_mul_f32_e32 v115, 0xbfb8aa3b, v115
	v_add_f32_e32 v114, 1.0, v114
	v_rcp_f32_e32 v114, v114
	v_exp_f32_e32 v115, v115
	s_nop 0
	v_lshlrev_b32_e32 v144, 16, v128
	v_add_f32_e32 v116, v116, v96
	v_mul_f32_e32 v114, v114, v141
	v_mul_f32_e32 v196, v114, v144
	v_add_f32_e32 v114, 1.0, v115
	v_mul_f32_e32 v115, 0x3fb8aa3b, v119
	v_rcp_f32_e32 v114, v114
	v_exp_f32_e32 v119, v115
	v_sqrt_f32_e32 v115, v170
	v_mul_f32_e32 v116, 0xbfb8aa3b, v116
	v_exp_f32_e32 v116, v116
	v_and_b32_e32 v128, 0xffff0000, v128
	v_mul_f32_e32 v114, v114, v115
	v_mul_f32_e32 v197, v114, v128
	v_add_f32_e32 v114, 1.0, v116
	v_mul_f32_e32 v115, 0x3fb8aa3b, v120
	v_add_f32_e32 v116, v117, v97
	v_rcp_f32_e32 v114, v114
	v_exp_f32_e32 v120, v115
	v_sqrt_f32_e32 v115, v171
	v_mul_f32_e32 v116, 0xbfb8aa3b, v116
	v_exp_f32_e32 v116, v116
	v_lshlrev_b32_e32 v117, 16, v129
	v_mul_f32_e32 v114, v114, v115
	v_mul_f32_e32 v198, v114, v117
	v_add_f32_e32 v114, 1.0, v116
	v_rcp_f32_e32 v114, v114
	v_sqrt_f32_e32 v115, v195
	v_mul_f32_e32 v118, 0x3fb8aa3b, v118
	v_mul_f32_e32 v116, 0x3fb8aa3b, v121
	v_lshlrev_b64 v[136:137], 9, v[136:137]
	v_exp_f32_e32 v118, v118
	v_exp_f32_e32 v121, v116
	v_and_b32_e32 v116, 0xffff0000, v129
	v_mul_f32_e32 v114, v114, v115
	v_mul_f32_e32 v199, v114, v116
	v_lshlrev_b64 v[116:117], 2, v[136:137]
	v_lshl_add_u64 v[114:115], s[20:21], 0, v[116:117]
	v_or_b32_e32 v128, 48, v140
	v_lshl_add_u64 v[114:115], v[114:115], 0, v[166:167]
	v_ashrrev_i32_e32 v129, 31, v128
	v_readlane_b32 s0, v255, 17
	global_store_dwordx4 v[114:115], v[118:121], off
	v_lshl_add_u64 v[116:117], s[22:23], 0, v[116:117]
	v_readlane_b32 s1, v255, 18
	v_lshlrev_b64 v[118:119], 10, v[128:129]
	v_lshl_add_u64 v[116:117], v[116:117], 0, v[166:167]
	v_lshl_add_u64 v[118:119], s[0:1], 0, v[118:119]
	global_store_dwordx4 v[116:117], v[196:199], off
	v_lshl_add_u64 v[118:119], v[168:169], 1, v[118:119]
	s_waitcnt vmcnt(10)
	s_nop 1
	v_mov_b32_e32 v120, v246
	v_mov_b32_e32 v121, v247
	v_add_f32_e32 v110, v110, v98
	v_mul_f32_e32 v110, 0xbfb8aa3b, v110
	v_exp_f32_e32 v110, v110
	s_mov_b32 s0, 0xbe800000
	v_add_f32_e32 v110, 1.0, v110
	v_rcp_f32_e32 v110, v110
	s_nop 0
	v_mul_f32_e32 v110, v110, v153
	v_add_f32_e32 v137, v110, v110
	v_cmp_nlt_f32_e32 vcc, s0, v137
	s_and_saveexec_b64 s[4:5], vcc
	s_xor_b64 s[8:9], exec, s[4:5]
	v_mul_f32_e32 v136, 0x3fb8aa3b, v137
	v_exp_f32_e32 v136, v136
	s_nop 0
	v_sub_f32_e32 v136, 1.0, v136
	s_andn2_saveexec_b64 s[8:9], s[8:9]
	v_fmamk_f32 v136, v137, 0x3c088889, v174
	v_fmaak_f32 v136, v137, v136, 0x3e2aaaab
	v_fma_f32 v136, v137, v136, 0.5
	v_fma_f32 v136, v137, v136, 1.0
	v_mul_f32_e64 v136, v136, -v137
	s_or_b64 exec, exec, s[8:9]
	v_add_f32_e32 v111, v111, v99
	v_mul_f32_e32 v111, 0xbfb8aa3b, v111
	v_exp_f32_e32 v111, v111
	s_nop 0
	v_add_f32_e32 v111, 1.0, v111
	v_rcp_f32_e32 v111, v111
	s_nop 0
	v_mul_f32_e32 v111, v111, v192
	v_add_f32_e32 v141, v111, v111
	v_cmp_nlt_f32_e32 vcc, s0, v141
	s_and_saveexec_b64 s[4:5], vcc
	s_xor_b64 s[8:9], exec, s[4:5]
	v_mul_f32_e32 v137, 0x3fb8aa3b, v141
	v_exp_f32_e32 v137, v137
	s_nop 0
	v_sub_f32_e32 v137, 1.0, v137
	s_andn2_saveexec_b64 s[8:9], s[8:9]
	v_fmamk_f32 v137, v141, 0x3c088889, v174
	v_fmaak_f32 v137, v141, v137, 0x3e2aaaab
	v_fma_f32 v137, v141, v137, 0.5
	v_fma_f32 v137, v141, v137, 1.0
	v_mul_f32_e64 v137, v137, -v141
	s_or_b64 exec, exec, s[8:9]
	v_add_f32_e32 v112, v112, v100
	v_mul_f32_e32 v112, 0xbfb8aa3b, v112
	v_exp_f32_e32 v112, v112
	s_nop 0
	v_add_f32_e32 v112, 1.0, v112
	v_rcp_f32_e32 v112, v112
	s_nop 0
	v_mul_f32_e32 v112, v112, v193
	v_add_f32_e32 v170, v112, v112
	v_cmp_nlt_f32_e32 vcc, s0, v170
	s_and_saveexec_b64 s[4:5], vcc
	s_xor_b64 s[8:9], exec, s[4:5]
	v_mul_f32_e32 v141, 0x3fb8aa3b, v170
	v_exp_f32_e32 v141, v141
	s_nop 0
	v_sub_f32_e32 v141, 1.0, v141
	s_andn2_saveexec_b64 s[8:9], s[8:9]
	v_fmamk_f32 v141, v170, 0x3c088889, v174
	v_fmaak_f32 v141, v170, v141, 0x3e2aaaab
	v_fma_f32 v141, v170, v141, 0.5
	v_fma_f32 v141, v170, v141, 1.0
	v_mul_f32_e64 v141, v141, -v170
	s_or_b64 exec, exec, s[8:9]
	v_add_f32_e32 v113, v113, v101
	v_mul_f32_e32 v113, 0xbfb8aa3b, v113
	v_exp_f32_e32 v113, v113
	s_nop 0
	v_add_f32_e32 v113, 1.0, v113
	v_rcp_f32_e32 v113, v113
	s_nop 0
	v_mul_f32_e32 v113, v113, v194
	v_add_f32_e32 v171, v113, v113
	v_cmp_nlt_f32_e32 vcc, s0, v171
	s_and_saveexec_b64 s[4:5], vcc
	s_xor_b64 s[8:9], exec, s[4:5]
	v_mul_f32_e32 v144, 0x3fb8aa3b, v171
	v_exp_f32_e32 v144, v144
	s_nop 0
	v_sub_f32_e32 v170, 1.0, v144
	s_andn2_saveexec_b64 s[8:9], s[8:9]
	v_fmamk_f32 v144, v171, 0x3c088889, v174
	v_fmaak_f32 v144, v171, v144, 0x3e2aaaab
	v_fma_f32 v144, v171, v144, 0.5
	v_fma_f32 v144, v171, v144, 1.0
	v_mul_f32_e64 v170, v144, -v171
	s_or_b64 exec, exec, s[8:9]
	v_add_f32_e32 v106, v106, v94
	v_mul_f32_e32 v106, 0xbfb8aa3b, v106
	v_exp_f32_e32 v106, v106
	v_add_f32_e32 v107, v107, v95
	v_sqrt_f32_e32 v136, v136
	v_mul_f32_e32 v107, 0xbfb8aa3b, v107
	v_add_f32_e32 v106, 1.0, v106
	v_rcp_f32_e32 v106, v106
	v_exp_f32_e32 v107, v107
	s_nop 0
	v_lshlrev_b32_e32 v144, 16, v120
	v_add_f32_e32 v108, v108, v96
	v_mul_f32_e32 v106, v106, v136
	v_mul_f32_e32 v196, v106, v144
	v_add_f32_e32 v106, 1.0, v107
	v_mul_f32_e32 v107, 0x3fb8aa3b, v111
	v_rcp_f32_e32 v106, v106
	v_exp_f32_e32 v111, v107
	v_sqrt_f32_e32 v107, v137
	v_mul_f32_e32 v108, 0xbfb8aa3b, v108
	v_exp_f32_e32 v108, v108
	v_and_b32_e32 v120, 0xffff0000, v120
	v_mul_f32_e32 v106, v106, v107
	v_mul_f32_e32 v197, v106, v120
	v_add_f32_e32 v106, 1.0, v108
	v_mul_f32_e32 v107, 0x3fb8aa3b, v112
	v_add_f32_e32 v108, v109, v97
	v_rcp_f32_e32 v106, v106
	v_exp_f32_e32 v112, v107
	v_sqrt_f32_e32 v107, v141
	v_mul_f32_e32 v108, 0xbfb8aa3b, v108
	v_exp_f32_e32 v108, v108
	v_lshlrev_b32_e32 v109, 16, v121
	v_mul_f32_e32 v106, v106, v107
	v_mul_f32_e32 v198, v106, v109
	v_add_f32_e32 v106, 1.0, v108
	v_rcp_f32_e32 v106, v106
	v_sqrt_f32_e32 v107, v170
	v_mul_f32_e32 v110, 0x3fb8aa3b, v110
	v_mul_f32_e32 v108, 0x3fb8aa3b, v113
	v_lshlrev_b64 v[128:129], 9, v[128:129]
	v_exp_f32_e32 v110, v110
	v_exp_f32_e32 v113, v108
	v_and_b32_e32 v108, 0xffff0000, v121
	v_mul_f32_e32 v106, v106, v107
	v_mul_f32_e32 v199, v106, v108
	v_lshlrev_b64 v[108:109], 2, v[128:129]
	v_lshl_add_u64 v[106:107], s[20:21], 0, v[108:109]
	v_add_u32_e32 v120, 0x80, v140
	v_lshl_add_u64 v[106:107], v[106:107], 0, v[166:167]
	v_ashrrev_i32_e32 v121, 31, v120
	v_readlane_b32 s0, v255, 17
	global_store_dwordx4 v[106:107], v[110:113], off
	v_lshl_add_u64 v[108:109], s[22:23], 0, v[108:109]
	v_readlane_b32 s1, v255, 18
	v_lshlrev_b64 v[110:111], 10, v[120:121]
	v_lshl_add_u64 v[108:109], v[108:109], 0, v[166:167]
	v_lshl_add_u64 v[110:111], s[0:1], 0, v[110:111]
	global_store_dwordx4 v[108:109], v[196:199], off
	v_lshl_add_u64 v[110:111], v[168:169], 1, v[110:111]
	s_waitcnt vmcnt(11)
	s_nop 1
	v_mov_b32_e32 v112, v248
	v_mov_b32_e32 v113, v249
	v_add_f32_e32 v102, v102, v98
	v_mul_f32_e32 v102, 0xbfb8aa3b, v102
	v_exp_f32_e32 v102, v102
	s_mov_b32 s0, 0xbe800000
	v_add_f32_e32 v102, 1.0, v102
	v_rcp_f32_e32 v102, v102
	s_nop 0
	v_mul_f32_e32 v102, v102, v153
	v_add_f32_e32 v129, v102, v102
	v_cmp_nlt_f32_e32 vcc, s0, v129
	s_and_saveexec_b64 s[4:5], vcc
	s_xor_b64 s[8:9], exec, s[4:5]
	v_mul_f32_e32 v128, 0x3fb8aa3b, v129
	v_exp_f32_e32 v128, v128
	s_nop 0
	v_sub_f32_e32 v128, 1.0, v128
	s_andn2_saveexec_b64 s[8:9], s[8:9]
	v_fmamk_f32 v128, v129, 0x3c088889, v174
	v_fmaak_f32 v128, v129, v128, 0x3e2aaaab
	v_fma_f32 v128, v129, v128, 0.5
	v_fma_f32 v128, v129, v128, 1.0
	v_mul_f32_e64 v128, v128, -v129
	s_or_b64 exec, exec, s[8:9]
	v_add_f32_e32 v103, v103, v99
	v_mul_f32_e32 v103, 0xbfb8aa3b, v103
	v_exp_f32_e32 v103, v103
	s_nop 0
	v_add_f32_e32 v103, 1.0, v103
	v_rcp_f32_e32 v103, v103
	s_nop 0
	v_mul_f32_e32 v103, v103, v192
	v_add_f32_e32 v136, v103, v103
	v_cmp_nlt_f32_e32 vcc, s0, v136
	s_and_saveexec_b64 s[4:5], vcc
	s_xor_b64 s[8:9], exec, s[4:5]
	v_mul_f32_e32 v129, 0x3fb8aa3b, v136
	v_exp_f32_e32 v129, v129
	s_nop 0
	v_sub_f32_e32 v129, 1.0, v129
	s_andn2_saveexec_b64 s[8:9], s[8:9]
	v_fmamk_f32 v129, v136, 0x3c088889, v174
	v_fmaak_f32 v129, v136, v129, 0x3e2aaaab
	v_fma_f32 v129, v136, v129, 0.5
	v_fma_f32 v129, v136, v129, 1.0
	v_mul_f32_e64 v129, v129, -v136
	s_or_b64 exec, exec, s[8:9]
	v_add_f32_e32 v104, v104, v100
	v_mul_f32_e32 v104, 0xbfb8aa3b, v104
	v_exp_f32_e32 v104, v104
	s_nop 0
	v_add_f32_e32 v104, 1.0, v104
	v_rcp_f32_e32 v104, v104
	s_nop 0
	v_mul_f32_e32 v104, v104, v193
	v_add_f32_e32 v137, v104, v104
	v_cmp_nlt_f32_e32 vcc, s0, v137
	s_and_saveexec_b64 s[4:5], vcc
	s_xor_b64 s[8:9], exec, s[4:5]
	v_mul_f32_e32 v136, 0x3fb8aa3b, v137
	v_exp_f32_e32 v136, v136
	s_nop 0
	v_sub_f32_e32 v136, 1.0, v136
	s_andn2_saveexec_b64 s[8:9], s[8:9]
	v_fmamk_f32 v136, v137, 0x3c088889, v174
	v_fmaak_f32 v136, v137, v136, 0x3e2aaaab
	v_fma_f32 v136, v137, v136, 0.5
	v_fma_f32 v136, v137, v136, 1.0
	v_mul_f32_e64 v136, v136, -v137
	s_or_b64 exec, exec, s[8:9]
	v_add_f32_e32 v105, v105, v101
	v_mul_f32_e32 v105, 0xbfb8aa3b, v105
	v_exp_f32_e32 v105, v105
	s_nop 0
	v_add_f32_e32 v105, 1.0, v105
	v_rcp_f32_e32 v105, v105
	s_nop 0
	v_mul_f32_e32 v105, v105, v194
	v_add_f32_e32 v141, v105, v105
	v_cmp_nlt_f32_e32 vcc, s0, v141
	s_and_saveexec_b64 s[4:5], vcc
	s_xor_b64 s[8:9], exec, s[4:5]
	v_mul_f32_e32 v137, 0x3fb8aa3b, v141
	v_exp_f32_e32 v137, v137
	s_nop 0
	v_sub_f32_e32 v137, 1.0, v137
	s_andn2_saveexec_b64 s[8:9], s[8:9]
	v_fmamk_f32 v137, v141, 0x3c088889, v174
	v_fmaak_f32 v137, v141, v137, 0x3e2aaaab
	v_fma_f32 v137, v141, v137, 0.5
	v_fma_f32 v137, v141, v137, 1.0
	v_mul_f32_e64 v137, v137, -v141
	s_or_b64 exec, exec, s[8:9]
	v_add_f32_e32 v90, v90, v94
	v_mul_f32_e32 v90, 0xbfb8aa3b, v90
	v_exp_f32_e32 v90, v90
	v_lshlrev_b64 v[170:171], 9, v[120:121]
	v_sqrt_f32_e32 v121, v128
	v_add_f32_e32 v91, v91, v95
	v_add_f32_e32 v90, 1.0, v90
	s_movk_i32 s4, 0x3f80
	v_and_b32_e32 v120, 0x7cf, v120
	v_rcp_f32_e32 v90, v90
	v_mul_f32_e32 v91, 0xbfb8aa3b, v91
	v_cmp_gt_i32_e32 vcc, s4, v140
	v_cmp_eq_u32_e64 s[8:9], 0, v120
	v_exp_f32_e32 v91, v91
	s_and_b64 s[8:9], vcc, s[8:9]
	v_cndmask_b32_e64 v121, v121, 1.0, s[8:9]
	s_nop 0
	v_lshlrev_b32_e32 v120, 16, v112
	v_mul_f32_e32 v90, v90, v121
	v_mul_f32_e32 v196, v90, v120
	v_add_f32_e32 v90, 1.0, v91
	v_mul_f32_e32 v91, 0x3fb8aa3b, v103
	v_exp_f32_e32 v103, v91
	v_and_b32_e32 v91, 0xffff0000, v112
	v_sqrt_f32_e32 v112, v129
	v_add_f32_e32 v92, v92, v96
	v_rcp_f32_e32 v90, v90
	v_mul_f32_e32 v92, 0xbfb8aa3b, v92
	v_exp_f32_e32 v92, v92
	v_cndmask_b32_e64 v112, v112, 1.0, s[8:9]
	v_mul_f32_e32 v90, v90, v112
	v_mul_f32_e32 v197, v90, v91
	v_add_f32_e32 v90, 1.0, v92
	v_sqrt_f32_e32 v92, v136
	v_add_f32_e32 v93, v93, v97
	v_rcp_f32_e32 v90, v90
	v_mul_f32_e32 v93, 0xbfb8aa3b, v93
	v_exp_f32_e32 v93, v93
	v_mul_f32_e32 v91, 0x3fb8aa3b, v104
	v_cndmask_b32_e64 v92, v92, 1.0, s[8:9]
	v_exp_f32_e32 v104, v91
	v_lshlrev_b32_e32 v91, 16, v113
	v_mul_f32_e32 v90, v90, v92
	v_mul_f32_e32 v198, v90, v91
	v_add_f32_e32 v90, 1.0, v93
	v_sqrt_f32_e32 v91, v137
	v_rcp_f32_e32 v90, v90
	v_mul_f32_e32 v102, 0x3fb8aa3b, v102
	v_mul_f32_e32 v92, 0x3fb8aa3b, v105
	v_cndmask_b32_e64 v91, v91, 1.0, s[8:9]
	v_exp_f32_e32 v102, v102
	v_exp_f32_e32 v105, v92
	v_and_b32_e32 v92, 0xffff0000, v113
	v_mul_f32_e32 v90, v90, v91
	v_mul_f32_e32 v199, v90, v92
	v_lshlrev_b64 v[92:93], 2, v[170:171]
	v_lshl_add_u64 v[90:91], s[20:21], 0, v[92:93]
	v_add_u32_e32 v112, 0x90, v140
	v_lshl_add_u64 v[90:91], v[90:91], 0, v[166:167]
	v_ashrrev_i32_e32 v113, 31, v112
	v_readlane_b32 s0, v255, 17
	global_store_dwordx4 v[90:91], v[102:105], off
	v_lshl_add_u64 v[92:93], s[22:23], 0, v[92:93]
	v_readlane_b32 s1, v255, 18
	v_lshlrev_b64 v[102:103], 10, v[112:113]
	v_lshl_add_u64 v[92:93], v[92:93], 0, v[166:167]
	v_lshl_add_u64 v[102:103], s[0:1], 0, v[102:103]
	global_store_dwordx4 v[92:93], v[196:199], off
	v_lshl_add_u64 v[102:103], v[168:169], 1, v[102:103]
	s_waitcnt vmcnt(12)
	s_nop 1
	v_mov_b32_e32 v104, v250
	v_mov_b32_e32 v105, v251
	v_add_f32_e32 v86, v86, v98
	v_mul_f32_e32 v86, 0xbfb8aa3b, v86
	v_exp_f32_e32 v86, v86
	s_mov_b32 s0, 0xbe800000
	v_add_f32_e32 v86, 1.0, v86
	v_rcp_f32_e32 v86, v86
	s_nop 0
	v_mul_f32_e32 v86, v86, v153
	v_add_f32_e32 v121, v86, v86
	v_cmp_nlt_f32_e32 vcc, s0, v121
	s_and_saveexec_b64 s[4:5], vcc
	s_xor_b64 s[30:31], exec, s[4:5]
	v_mul_f32_e32 v120, 0x3fb8aa3b, v121
	v_exp_f32_e32 v120, v120
	s_nop 0
	v_sub_f32_e32 v120, 1.0, v120
	s_andn2_saveexec_b64 s[30:31], s[30:31]
	v_fmamk_f32 v120, v121, 0x3c088889, v174
	v_fmaak_f32 v120, v121, v120, 0x3e2aaaab
	v_fma_f32 v120, v121, v120, 0.5
	v_fma_f32 v120, v121, v120, 1.0
	v_mul_f32_e64 v120, v120, -v121
	s_or_b64 exec, exec, s[30:31]
	v_add_f32_e32 v87, v87, v99
	v_mul_f32_e32 v87, 0xbfb8aa3b, v87
	v_exp_f32_e32 v87, v87
	s_nop 0
	v_add_f32_e32 v87, 1.0, v87
	v_rcp_f32_e32 v87, v87
	s_nop 0
	v_mul_f32_e32 v87, v87, v192
	v_add_f32_e32 v128, v87, v87
	v_cmp_nlt_f32_e32 vcc, s0, v128
	s_and_saveexec_b64 s[4:5], vcc
	s_xor_b64 s[30:31], exec, s[4:5]
	v_mul_f32_e32 v121, 0x3fb8aa3b, v128
	v_exp_f32_e32 v121, v121
	s_nop 0
	v_sub_f32_e32 v121, 1.0, v121
	s_andn2_saveexec_b64 s[30:31], s[30:31]
	v_fmamk_f32 v121, v128, 0x3c088889, v174
	v_fmaak_f32 v121, v128, v121, 0x3e2aaaab
	v_fma_f32 v121, v128, v121, 0.5
	v_fma_f32 v121, v128, v121, 1.0
	v_mul_f32_e64 v121, v121, -v128
	s_or_b64 exec, exec, s[30:31]
	v_add_f32_e32 v88, v88, v100
	v_mul_f32_e32 v88, 0xbfb8aa3b, v88
	v_exp_f32_e32 v88, v88
	s_nop 0
	v_add_f32_e32 v88, 1.0, v88
	v_rcp_f32_e32 v88, v88
	s_nop 0
	v_mul_f32_e32 v88, v88, v193
	v_add_f32_e32 v129, v88, v88
	v_cmp_nlt_f32_e32 vcc, s0, v129
	s_and_saveexec_b64 s[4:5], vcc
	s_xor_b64 s[30:31], exec, s[4:5]
	v_mul_f32_e32 v128, 0x3fb8aa3b, v129
	v_exp_f32_e32 v128, v128
	s_nop 0
	v_sub_f32_e32 v128, 1.0, v128
	s_andn2_saveexec_b64 s[30:31], s[30:31]
	v_fmamk_f32 v128, v129, 0x3c088889, v174
	v_fmaak_f32 v128, v129, v128, 0x3e2aaaab
	v_fma_f32 v128, v129, v128, 0.5
	v_fma_f32 v128, v129, v128, 1.0
	v_mul_f32_e64 v128, v128, -v129
	s_or_b64 exec, exec, s[30:31]
	v_add_f32_e32 v89, v89, v101
	v_mul_f32_e32 v89, 0xbfb8aa3b, v89
	v_exp_f32_e32 v89, v89
	s_nop 0
	v_add_f32_e32 v89, 1.0, v89
	v_rcp_f32_e32 v89, v89
	s_nop 0
	v_mul_f32_e32 v89, v89, v194
	v_add_f32_e32 v136, v89, v89
	v_cmp_nlt_f32_e32 vcc, s0, v136
	s_and_saveexec_b64 s[4:5], vcc
	s_xor_b64 s[30:31], exec, s[4:5]
	v_mul_f32_e32 v129, 0x3fb8aa3b, v136
	v_exp_f32_e32 v129, v129
	s_nop 0
	v_sub_f32_e32 v129, 1.0, v129
	s_andn2_saveexec_b64 s[30:31], s[30:31]
	v_fmamk_f32 v129, v136, 0x3c088889, v174
	v_fmaak_f32 v129, v136, v129, 0x3e2aaaab
	v_fma_f32 v129, v136, v129, 0.5
	v_fma_f32 v129, v136, v129, 1.0
	v_mul_f32_e64 v129, v129, -v136
	s_or_b64 exec, exec, s[30:31]
	v_add_f32_e32 v82, v82, v94
	v_mul_f32_e32 v82, 0xbfb8aa3b, v82
	v_exp_f32_e32 v82, v82
	v_add_f32_e32 v83, v83, v95
	v_sqrt_f32_e32 v120, v120
	v_mul_f32_e32 v83, 0xbfb8aa3b, v83
	v_add_f32_e32 v82, 1.0, v82
	v_rcp_f32_e32 v82, v82
	v_exp_f32_e32 v83, v83
	s_nop 0
	v_lshlrev_b32_e32 v136, 16, v104
	v_add_f32_e32 v84, v84, v96
	v_mul_f32_e32 v82, v82, v120
	v_mul_f32_e32 v196, v82, v136
	v_add_f32_e32 v82, 1.0, v83
	v_mul_f32_e32 v83, 0x3fb8aa3b, v87
	v_rcp_f32_e32 v82, v82
	v_exp_f32_e32 v87, v83
	v_sqrt_f32_e32 v83, v121
	v_mul_f32_e32 v84, 0xbfb8aa3b, v84
	v_exp_f32_e32 v84, v84
	v_and_b32_e32 v104, 0xffff0000, v104
	v_mul_f32_e32 v82, v82, v83
	v_mul_f32_e32 v197, v82, v104
	v_add_f32_e32 v82, 1.0, v84
	v_mul_f32_e32 v83, 0x3fb8aa3b, v88
	v_add_f32_e32 v84, v85, v97
	v_rcp_f32_e32 v82, v82
	v_exp_f32_e32 v88, v83
	v_sqrt_f32_e32 v83, v128
	v_mul_f32_e32 v84, 0xbfb8aa3b, v84
	v_exp_f32_e32 v84, v84
	v_lshlrev_b32_e32 v85, 16, v105
	v_mul_f32_e32 v82, v82, v83
	v_mul_f32_e32 v198, v82, v85
	v_add_f32_e32 v82, 1.0, v84
	v_rcp_f32_e32 v82, v82
	v_sqrt_f32_e32 v83, v129
	v_mul_f32_e32 v86, 0x3fb8aa3b, v86
	v_mul_f32_e32 v84, 0x3fb8aa3b, v89
	v_lshlrev_b64 v[112:113], 9, v[112:113]
	v_exp_f32_e32 v86, v86
	v_exp_f32_e32 v89, v84
	v_and_b32_e32 v84, 0xffff0000, v105
	v_mul_f32_e32 v82, v82, v83
	v_mul_f32_e32 v199, v82, v84
	v_lshlrev_b64 v[84:85], 2, v[112:113]
	v_lshl_add_u64 v[82:83], s[20:21], 0, v[84:85]
	v_add_u32_e32 v104, 0xa0, v140
	v_lshl_add_u64 v[82:83], v[82:83], 0, v[166:167]
	v_ashrrev_i32_e32 v105, 31, v104
	v_readlane_b32 s0, v255, 17
	global_store_dwordx4 v[82:83], v[86:89], off
	v_lshl_add_u64 v[84:85], s[22:23], 0, v[84:85]
	v_readlane_b32 s1, v255, 18
	v_lshlrev_b64 v[86:87], 10, v[104:105]
	v_lshl_add_u64 v[84:85], v[84:85], 0, v[166:167]
	v_lshl_add_u64 v[86:87], s[0:1], 0, v[86:87]
	global_store_dwordx4 v[84:85], v[196:199], off
	v_lshl_add_u64 v[86:87], v[168:169], 1, v[86:87]
	s_waitcnt vmcnt(13)
	s_nop 1
	v_mov_b32_e32 v88, v180
	v_mov_b32_e32 v89, v181
	v_add_f32_e32 v78, v78, v98
	v_mul_f32_e32 v78, 0xbfb8aa3b, v78
	v_exp_f32_e32 v78, v78
	s_mov_b32 s0, 0xbe800000
	v_add_f32_e32 v78, 1.0, v78
	v_rcp_f32_e32 v78, v78
	s_nop 0
	v_mul_f32_e32 v78, v78, v153
	v_add_f32_e32 v113, v78, v78
	v_cmp_nlt_f32_e32 vcc, s0, v113
	s_and_saveexec_b64 s[4:5], vcc
	s_xor_b64 s[30:31], exec, s[4:5]
	v_mul_f32_e32 v112, 0x3fb8aa3b, v113
	v_exp_f32_e32 v112, v112
	s_nop 0
	v_sub_f32_e32 v112, 1.0, v112
	s_andn2_saveexec_b64 s[30:31], s[30:31]
	v_fmamk_f32 v112, v113, 0x3c088889, v174
	v_fmaak_f32 v112, v113, v112, 0x3e2aaaab
	v_fma_f32 v112, v113, v112, 0.5
	v_fma_f32 v112, v113, v112, 1.0
	v_mul_f32_e64 v112, v112, -v113
	s_or_b64 exec, exec, s[30:31]
	v_add_f32_e32 v79, v79, v99
	v_mul_f32_e32 v79, 0xbfb8aa3b, v79
	v_exp_f32_e32 v79, v79
	s_nop 0
	v_add_f32_e32 v79, 1.0, v79
	v_rcp_f32_e32 v79, v79
	s_nop 0
	v_mul_f32_e32 v79, v79, v192
	v_add_f32_e32 v120, v79, v79
	v_cmp_nlt_f32_e32 vcc, s0, v120
	s_and_saveexec_b64 s[4:5], vcc
	s_xor_b64 s[30:31], exec, s[4:5]
	v_mul_f32_e32 v113, 0x3fb8aa3b, v120
	v_exp_f32_e32 v113, v113
	s_nop 0
	v_sub_f32_e32 v113, 1.0, v113
	s_andn2_saveexec_b64 s[30:31], s[30:31]
	v_fmamk_f32 v113, v120, 0x3c088889, v174
	v_fmaak_f32 v113, v120, v113, 0x3e2aaaab
	v_fma_f32 v113, v120, v113, 0.5
	v_fma_f32 v113, v120, v113, 1.0
	v_mul_f32_e64 v113, v113, -v120
	s_or_b64 exec, exec, s[30:31]
	v_add_f32_e32 v80, v80, v100
	v_mul_f32_e32 v80, 0xbfb8aa3b, v80
	v_exp_f32_e32 v80, v80
	s_nop 0
	v_add_f32_e32 v80, 1.0, v80
	v_rcp_f32_e32 v80, v80
	s_nop 0
	v_mul_f32_e32 v80, v80, v193
	v_add_f32_e32 v121, v80, v80
	v_cmp_nlt_f32_e32 vcc, s0, v121
	s_and_saveexec_b64 s[4:5], vcc
	s_xor_b64 s[30:31], exec, s[4:5]
	v_mul_f32_e32 v120, 0x3fb8aa3b, v121
	v_exp_f32_e32 v120, v120
	s_nop 0
	v_sub_f32_e32 v120, 1.0, v120
	s_andn2_saveexec_b64 s[30:31], s[30:31]
	v_fmamk_f32 v120, v121, 0x3c088889, v174
	v_fmaak_f32 v120, v121, v120, 0x3e2aaaab
	v_fma_f32 v120, v121, v120, 0.5
	v_fma_f32 v120, v121, v120, 1.0
	v_mul_f32_e64 v120, v120, -v121
	s_or_b64 exec, exec, s[30:31]
	v_add_f32_e32 v81, v81, v101
	v_mul_f32_e32 v81, 0xbfb8aa3b, v81
	v_exp_f32_e32 v81, v81
	s_nop 0
	v_add_f32_e32 v81, 1.0, v81
	v_rcp_f32_e32 v81, v81
	s_nop 0
	v_mul_f32_e32 v81, v81, v194
	v_add_f32_e32 v128, v81, v81
	v_cmp_nlt_f32_e32 vcc, s0, v128
	s_and_saveexec_b64 s[4:5], vcc
	s_xor_b64 s[30:31], exec, s[4:5]
	v_mul_f32_e32 v121, 0x3fb8aa3b, v128
	v_exp_f32_e32 v121, v121
	s_nop 0
	v_sub_f32_e32 v121, 1.0, v121
	s_andn2_saveexec_b64 s[30:31], s[30:31]
	v_fmamk_f32 v121, v128, 0x3c088889, v174
	v_fmaak_f32 v121, v128, v121, 0x3e2aaaab
	v_fma_f32 v121, v128, v121, 0.5
	v_fma_f32 v121, v128, v121, 1.0
	v_mul_f32_e64 v121, v121, -v128
	s_or_b64 exec, exec, s[30:31]
	v_add_f32_e32 v74, v74, v94
	v_mul_f32_e32 v74, 0xbfb8aa3b, v74
	v_exp_f32_e32 v74, v74
	v_sqrt_f32_e32 v112, v112
	v_add_f32_e32 v76, v76, v96
	v_mul_f32_e32 v78, 0x3fb8aa3b, v78
	v_add_f32_e32 v74, 1.0, v74
	v_rcp_f32_e32 v129, v74
	v_add_f32_e32 v74, v75, v95
	v_mul_f32_e32 v74, 0xbfb8aa3b, v74
	v_exp_f32_e32 v75, v74
	v_mul_f32_e32 v76, 0xbfb8aa3b, v76
	v_exp_f32_e32 v74, v78
	v_mul_f32_e32 v78, v129, v112
	v_add_f32_e32 v75, 1.0, v75
	v_rcp_f32_e32 v112, v75
	v_mul_f32_e32 v75, 0x3fb8aa3b, v79
	v_sqrt_f32_e32 v79, v113
	v_exp_f32_e32 v76, v76
	v_add_f32_e32 v77, v77, v97
	s_nop 0
	v_lshlrev_b32_e32 v128, 16, v88
	v_and_b32_e32 v88, 0xffff0000, v88
	v_mul_f32_e32 v79, v112, v79
	v_add_f32_e32 v76, 1.0, v76
	v_mul_f32_e32 v77, 0xbfb8aa3b, v77
	v_mul_f32_e32 v79, v79, v88
	v_rcp_f32_e32 v88, v76
	v_mul_f32_e32 v76, 0x3fb8aa3b, v80
	v_sqrt_f32_e32 v80, v120
	v_exp_f32_e32 v77, v77
	v_lshlrev_b32_e32 v112, 16, v89
	v_lshlrev_b64 v[104:105], 9, v[104:105]
	v_mul_f32_e32 v80, v88, v80
	v_add_f32_e32 v77, 1.0, v77
	v_mul_f32_e32 v80, v80, v112
	v_rcp_f32_e32 v88, v77
	v_sqrt_f32_e32 v112, v121
	v_mul_f32_e32 v77, 0x3fb8aa3b, v81
	v_exp_f32_e32 v75, v75
	v_exp_f32_e32 v76, v76
	v_exp_f32_e32 v77, v77
	v_and_b32_e32 v81, 0xffff0000, v89
	v_mul_f32_e32 v88, v88, v112
	v_lshlrev_b64 v[104:105], 2, v[104:105]
	v_mul_f32_e32 v81, v88, v81
	v_lshl_add_u64 v[88:89], s[20:21], 0, v[104:105]
	v_lshl_add_u64 v[88:89], v[88:89], 0, v[166:167]
	global_store_dwordx4 v[88:89], v[74:77], off
	v_readlane_b32 s0, v255, 17
	v_readlane_b32 s1, v255, 18
	v_add_u32_e32 v76, 0xb0, v140
	v_lshl_add_u64 v[74:75], s[22:23], 0, v[104:105]
	v_ashrrev_i32_e32 v77, 31, v76
	v_lshl_add_u64 v[104:105], v[74:75], 0, v[166:167]
	v_lshlrev_b64 v[74:75], 10, v[76:77]
	v_mul_f32_e32 v78, v78, v128
	v_lshl_add_u64 v[74:75], s[0:1], 0, v[74:75]
	global_store_dwordx4 v[104:105], v[78:81], off
	v_lshl_add_u64 v[112:113], v[168:169], 1, v[74:75]
	s_waitcnt vmcnt(14)
	s_nop 1
	v_mov_b32_e32 v74, v182
	v_mov_b32_e32 v75, v183
	v_add_f32_e32 v70, v70, v98
	v_mul_f32_e32 v70, 0xbfb8aa3b, v70
	v_exp_f32_e32 v70, v70
	s_mov_b32 s0, 0xbe800000
	v_add_f32_e32 v70, 1.0, v70
	v_rcp_f32_e32 v70, v70
	s_nop 0
	v_mul_f32_e32 v70, v70, v153
	v_add_f32_e32 v79, v70, v70
	v_cmp_nlt_f32_e32 vcc, s0, v79
	s_and_saveexec_b64 s[4:5], vcc
	s_xor_b64 s[30:31], exec, s[4:5]
	v_mul_f32_e32 v78, 0x3fb8aa3b, v79
	v_exp_f32_e32 v78, v78
	s_nop 0
	v_sub_f32_e32 v78, 1.0, v78
	s_andn2_saveexec_b64 s[30:31], s[30:31]
	v_fmamk_f32 v78, v79, 0x3c088889, v174
	v_fmaak_f32 v78, v79, v78, 0x3e2aaaab
	v_fma_f32 v78, v79, v78, 0.5
	v_fma_f32 v78, v79, v78, 1.0
	v_mul_f32_e64 v78, v78, -v79
	s_or_b64 exec, exec, s[30:31]
	v_add_f32_e32 v71, v71, v99
	v_mul_f32_e32 v71, 0xbfb8aa3b, v71
	v_exp_f32_e32 v71, v71
	s_nop 0
	v_add_f32_e32 v71, 1.0, v71
	v_rcp_f32_e32 v71, v71
	s_nop 0
	v_mul_f32_e32 v71, v71, v192
	v_add_f32_e32 v80, v71, v71
	v_cmp_nlt_f32_e32 vcc, s0, v80
	s_and_saveexec_b64 s[4:5], vcc
	s_xor_b64 s[30:31], exec, s[4:5]
	v_mul_f32_e32 v79, 0x3fb8aa3b, v80
	v_exp_f32_e32 v79, v79
	s_nop 0
	v_sub_f32_e32 v79, 1.0, v79
	s_andn2_saveexec_b64 s[30:31], s[30:31]
	v_fmamk_f32 v79, v80, 0x3c088889, v174
	v_fmaak_f32 v79, v80, v79, 0x3e2aaaab
	v_fma_f32 v79, v80, v79, 0.5
	v_fma_f32 v79, v80, v79, 1.0
	v_mul_f32_e64 v79, v79, -v80
	s_or_b64 exec, exec, s[30:31]
	v_add_f32_e32 v72, v72, v100
	v_mul_f32_e32 v72, 0xbfb8aa3b, v72
	v_exp_f32_e32 v72, v72
	s_nop 0
	v_add_f32_e32 v72, 1.0, v72
	v_rcp_f32_e32 v72, v72
	s_nop 0
	v_mul_f32_e32 v72, v72, v193
	v_add_f32_e32 v81, v72, v72
	v_cmp_nlt_f32_e32 vcc, s0, v81
	s_and_saveexec_b64 s[4:5], vcc
	s_xor_b64 s[30:31], exec, s[4:5]
	v_mul_f32_e32 v80, 0x3fb8aa3b, v81
	v_exp_f32_e32 v80, v80
	s_nop 0
	v_sub_f32_e32 v80, 1.0, v80
	s_andn2_saveexec_b64 s[30:31], s[30:31]
	v_fmamk_f32 v80, v81, 0x3c088889, v174
	v_fmaak_f32 v80, v81, v80, 0x3e2aaaab
	v_fma_f32 v80, v81, v80, 0.5
	v_fma_f32 v80, v81, v80, 1.0
	v_mul_f32_e64 v80, v80, -v81
	s_or_b64 exec, exec, s[30:31]
	v_add_f32_e32 v73, v73, v101
	v_mul_f32_e32 v73, 0xbfb8aa3b, v73
	v_exp_f32_e32 v73, v73
	s_nop 0
	v_add_f32_e32 v73, 1.0, v73
	v_rcp_f32_e32 v73, v73
	s_nop 0
	v_mul_f32_e32 v73, v73, v194
	v_add_f32_e32 v98, v73, v73
	v_cmp_nlt_f32_e32 vcc, s0, v98
	s_and_saveexec_b64 s[4:5], vcc
	s_xor_b64 s[30:31], exec, s[4:5]
	v_mul_f32_e32 v81, 0x3fb8aa3b, v98
	v_exp_f32_e32 v81, v81
	s_nop 0
	v_sub_f32_e32 v81, 1.0, v81
	s_andn2_saveexec_b64 s[30:31], s[30:31]
	v_fmamk_f32 v81, v98, 0x3c088889, v174
	v_fmaak_f32 v81, v98, v81, 0x3e2aaaab
	v_fma_f32 v81, v98, v81, 0.5
	v_fma_f32 v81, v98, v81, 1.0
	v_mul_f32_e64 v81, v81, -v98
	s_or_b64 exec, exec, s[30:31]
	v_add_f32_e32 v66, v66, v94
	v_mul_f32_e32 v66, 0xbfb8aa3b, v66
	v_exp_f32_e32 v66, v66
	v_sqrt_f32_e32 v78, v78
	v_add_f32_e32 v68, v68, v96
	v_mul_f32_e32 v70, 0x3fb8aa3b, v70
	v_add_f32_e32 v66, 1.0, v66
	v_rcp_f32_e32 v98, v66
	v_add_f32_e32 v66, v67, v95
	v_mul_f32_e32 v66, 0xbfb8aa3b, v66
	v_exp_f32_e32 v67, v66
	v_mul_f32_e32 v68, 0xbfb8aa3b, v68
	v_exp_f32_e32 v66, v70
	v_mul_f32_e32 v70, v98, v78
	v_add_f32_e32 v67, 1.0, v67
	v_rcp_f32_e32 v78, v67
	v_mul_f32_e32 v67, 0x3fb8aa3b, v71
	v_sqrt_f32_e32 v71, v79
	v_exp_f32_e32 v68, v68
	v_add_f32_e32 v69, v69, v97
	s_nop 0
	v_lshlrev_b32_e32 v94, 16, v74
	v_and_b32_e32 v74, 0xffff0000, v74
	v_mul_f32_e32 v71, v78, v71
	v_add_f32_e32 v68, 1.0, v68
	v_mul_f32_e32 v69, 0xbfb8aa3b, v69
	v_mul_f32_e32 v71, v71, v74
	v_rcp_f32_e32 v74, v68
	v_mul_f32_e32 v68, 0x3fb8aa3b, v72
	v_sqrt_f32_e32 v72, v80
	v_exp_f32_e32 v69, v69
	v_lshlrev_b32_e32 v78, 16, v75
	v_lshlrev_b64 v[76:77], 9, v[76:77]
	v_mul_f32_e32 v72, v74, v72
	v_add_f32_e32 v69, 1.0, v69
	v_mul_f32_e32 v72, v72, v78
	v_rcp_f32_e32 v74, v69
	v_sqrt_f32_e32 v78, v81
	v_mul_f32_e32 v69, 0x3fb8aa3b, v73
	v_exp_f32_e32 v67, v67
	v_exp_f32_e32 v68, v68
	v_exp_f32_e32 v69, v69
	v_and_b32_e32 v73, 0xffff0000, v75
	v_mul_f32_e32 v74, v74, v78
	v_mul_f32_e32 v73, v74, v73
	v_lshlrev_b64 v[74:75], 2, v[76:77]
	v_lshl_add_u64 v[76:77], s[20:21], 0, v[74:75]
	v_lshl_add_u64 v[78:79], v[76:77], 0, v[166:167]
	global_store_dwordx4 v[78:79], v[66:69], off
	v_mul_f32_e32 v70, v70, v94
	s_mov_b32 s0, 0xc1a00000
	v_lshl_add_u64 v[66:67], s[22:23], 0, v[74:75]
	v_lshl_add_u64 v[80:81], v[66:67], 0, v[166:167]
	global_store_dwordx4 v[80:81], v[70:73], off
	global_load_dwordx4 v[74:77], v[164:165], off offset:64
	s_nop 0
	global_load_dwordx4 v[70:73], v[160:161], off offset:64
	global_load_dwordx4 v[66:69], v[162:163], off offset:64
	s_waitcnt vmcnt(0)
	v_xor_b32_e32 v94, 0x80000000, v74
	v_cmp_ngt_f32_e32 vcc, s0, v74
	s_and_saveexec_b64 s[30:31], vcc
	s_cbranch_execz .LBB0_455
	v_mul_f32_e32 v74, 0xbfb8aa3b, v74
	v_exp_f32_e32 v74, v74
	s_mov_b32 s0, 0x3f2aaaab
	v_add_f32_e32 v96, 1.0, v74
	v_frexp_mant_f32_e32 v98, v96
	v_cvt_f64_f32_e32 v[94:95], v96
	v_frexp_exp_i32_f64_e32 v94, v[94:95]
	v_cmp_gt_f32_e32 vcc, s0, v98
	v_add_f32_e32 v97, -1.0, v96
	v_sub_f32_e32 v99, v97, v96
	v_subbrev_co_u32_e32 v120, vcc, 0, v94, vcc
	v_sub_u32_e32 v94, 0, v120
	v_sub_f32_e32 v97, v74, v97
	v_add_f32_e32 v99, 1.0, v99
	v_ldexp_f32 v95, v96, v94
	v_add_f32_e32 v97, v97, v99
	v_add_f32_e32 v96, -1.0, v95
	v_add_f32_e32 v98, 1.0, v95
	v_ldexp_f32 v94, v97, v94
	v_add_f32_e32 v97, 1.0, v96
	v_add_f32_e32 v99, -1.0, v98
	v_sub_f32_e32 v97, v95, v97
	v_sub_f32_e32 v95, v95, v99
	v_add_f32_e32 v97, v94, v97
	v_add_f32_e32 v94, v94, v95
	v_add_f32_e32 v121, v98, v94
	v_rcp_f32_e32 v129, v121
	v_sub_f32_e32 v95, v121, v98
	v_sub_f32_e32 v128, v94, v95
	v_add_f32_e32 v95, v96, v97
	v_mul_f32_e32 v137, v95, v129
	v_sub_f32_e32 v94, v95, v96
	v_mul_f32_e32 v96, v121, v137
	v_fma_f32 v98, v137, v121, -v96
	v_fmac_f32_e32 v98, v137, v128
	v_sub_f32_e32 v136, v97, v94
	v_add_f32_e32 v94, v96, v98
	v_sub_f32_e32 v97, v95, v94
	v_pk_add_f32 v[100:101], v[94:95], v[96:97] neg_lo:[0,1] neg_hi:[0,1]
	v_mov_b32_e32 v99, v94
	v_pk_add_f32 v[94:95], v[100:101], v[98:99] neg_lo:[0,1] neg_hi:[0,1]
	s_mov_b32 s0, 0x3f317218
	v_add_f32_e32 v95, v136, v95
	v_add_f32_e32 v94, v94, v95
	v_add_f32_e32 v95, v97, v94
	v_mul_f32_e32 v136, v129, v95
	v_mul_f32_e32 v96, v121, v136
	v_fma_f32 v98, v136, v121, -v96
	v_fmac_f32_e32 v98, v136, v128
	v_sub_f32_e32 v97, v97, v95
	v_add_f32_e32 v121, v94, v97
	v_add_f32_e32 v94, v96, v98
	v_sub_f32_e32 v97, v95, v94
	v_pk_add_f32 v[100:101], v[94:95], v[96:97] neg_lo:[0,1] neg_hi:[0,1]
	v_mov_b32_e32 v99, v94
	v_pk_add_f32 v[94:95], v[100:101], v[98:99] neg_lo:[0,1] neg_hi:[0,1]
	s_nop 0
	v_add_f32_e32 v95, v121, v95
	v_add_f32_e32 v94, v94, v95
	v_add_f32_e32 v95, v137, v136
	v_add_f32_e32 v94, v97, v94
	v_sub_f32_e32 v96, v95, v137
	v_mul_f32_e32 v94, v129, v94
	v_sub_f32_e32 v96, v136, v96
	v_add_f32_e32 v96, v96, v94
	v_add_f32_e32 v98, v95, v96
	v_mul_f32_e32 v99, v98, v98
	v_fmamk_f32 v94, v99, 0x3e9b6dac, v184
	v_fmaak_f32 v153, v99, v94, 0x3f2aaada
	v_cvt_f32_i32_e32 v94, v120
	v_sub_f32_e32 v95, v98, v95
	v_sub_f32_e32 v95, v96, v95
	v_ldexp_f32 v100, v95, 1
	v_mul_f32_e32 v95, v98, v99
	v_ldexp_f32 v97, v98, 1
	v_pk_mul_f32 v[98:99], v[94:95], v[152:153]
	s_nop 0
	v_fma_f32 v96, v94, s0, -v98
	v_fmac_f32_e32 v96, 0xb102e308, v94
	v_pk_add_f32 v[94:95], v[98:99], v[96:97]
	s_mov_b32 s0, 0x7f800000
	v_sub_f32_e32 v97, v95, v97
	v_sub_f32_e32 v97, v99, v97
	v_add_f32_e32 v101, v100, v97
	v_mov_b32_e32 v100, v98
	v_pk_add_f32 v[98:99], v[94:95], v[98:99] neg_lo:[0,1] neg_hi:[0,1]
	v_pk_add_f32 v[120:121], v[94:95], v[100:101]
	v_mov_b32_e32 v97, v94
	v_mov_b32_e32 v99, v121
	v_pk_add_f32 v[128:129], v[96:97], v[98:99] neg_lo:[0,1] neg_hi:[0,1]
	v_pk_add_f32 v[96:97], v[96:97], v[98:99]
	v_mov_b32_e32 v100, v101
	v_pk_add_f32 v[98:99], v[96:97], v[94:95] op_sel:[1,0] op_sel_hi:[0,1] neg_lo:[0,1] neg_hi:[0,1]
	v_pk_add_f32 v[136:137], v[120:121], v[98:99] op_sel_hi:[1,0] neg_lo:[0,1] neg_hi:[0,1]
	v_mov_b32_e32 v120, v121
	v_mov_b32_e32 v121, v97
	v_pk_mov_b32 v[98:99], v[94:95], v[98:99] op_sel:[1,0]
	v_mov_b32_e32 v101, v94
	v_pk_add_f32 v[98:99], v[120:121], v[98:99] neg_lo:[0,1] neg_hi:[0,1]
	v_mov_b32_e32 v136, v128
	v_pk_add_f32 v[94:95], v[100:101], v[98:99] neg_lo:[0,1] neg_hi:[0,1]
	v_mov_b32_e32 v129, v97
	v_pk_add_f32 v[98:99], v[136:137], v[94:95]
	v_cmp_neq_f32_e32 vcc, s0, v74
	v_pk_add_f32 v[100:101], v[98:99], v[98:99] op_sel:[0,1] op_sel_hi:[1,0]
	s_mov_b32 s0, 0x33800000
	v_pk_add_f32 v[96:97], v[96:97], v[100:101] op_sel:[1,0] op_sel_hi:[0,1]
	v_mov_b32_e32 v99, v96
	v_pk_add_f32 v[120:121], v[98:99], v[128:129] neg_lo:[0,1] neg_hi:[0,1]
	v_mov_b32_e32 v95, v100
	v_sub_f32_e32 v97, v98, v120
	v_pk_add_f32 v[94:95], v[94:95], v[120:121] neg_lo:[0,1] neg_hi:[0,1]
	v_sub_f32_e32 v97, v128, v97
	v_add_f32_e32 v94, v94, v97
	v_add_f32_e32 v94, v94, v95
	v_add_f32_e32 v94, v96, v94
	v_cndmask_b32_e32 v94, v175, v94, vcc
	v_cmp_ngt_f32_e32 vcc, -1.0, v74
	s_nop 1
	v_cndmask_b32_e32 v94, v176, v94, vcc
	v_cmp_neq_f32_e32 vcc, -1.0, v74
	s_nop 1
	v_cndmask_b32_e32 v94, v179, v94, vcc
	v_cmp_lt_f32_e64 vcc, |v74|, s0
	s_nop 1
	v_cndmask_b32_e32 v94, v94, v74, vcc

.LBB0_461:
	s_or_b64 exec, exec, s[30:31]
	global_load_dwordx2 v[74:75], v[138:139], off offset:32
	s_mov_b32 s99, 0
	s_mov_b32 s98, 0x4000
	v_lshl_add_u64 v[242:243], s[98:99], 0, v[138:139]
	global_load_dwordx2 v[242:243], v[242:243], off offset:32
	s_mov_b32 s98, 0x8000
	v_lshl_add_u64 v[244:245], s[98:99], 0, v[138:139]
	global_load_dwordx2 v[244:245], v[244:245], off offset:32
	s_mov_b32 s98, 0xc000
	v_lshl_add_u64 v[246:247], s[98:99], 0, v[138:139]
	global_load_dwordx2 v[246:247], v[246:247], off offset:32
	s_mov_b32 s98, 0x20000
	v_lshl_add_u64 v[248:249], s[98:99], 0, v[138:139]
	global_load_dwordx2 v[248:249], v[248:249], off offset:32
	s_mov_b32 s98, 0x24000
	v_lshl_add_u64 v[250:251], s[98:99], 0, v[138:139]
	global_load_dwordx2 v[250:251], v[250:251], off offset:32
	s_mov_b32 s98, 0x28000
	v_lshl_add_u64 v[180:181], s[98:99], 0, v[138:139]
	global_load_dwordx2 v[180:181], v[180:181], off offset:32
	s_mov_b32 s98, 0x2c000
	v_lshl_add_u64 v[182:183], s[98:99], 0, v[138:139]
	global_load_dwordx2 v[182:183], v[182:183], off offset:32
	v_add_f32_e32 v62, v62, v70
	v_mul_f32_e32 v62, 0xbfb8aa3b, v62
	v_exp_f32_e32 v62, v62
	s_mov_b32 s0, 0xbe800000
	v_add_f32_e32 v62, 1.0, v62
	v_rcp_f32_e32 v76, v62
	v_mul_f32_e32 v62, 0xc1000000, v94
	v_mul_f32_e32 v76, v76, v62
	v_add_f32_e32 v94, v76, v76
	v_cmp_nlt_f32_e32 vcc, s0, v94
	s_and_saveexec_b64 s[4:5], vcc
	s_xor_b64 s[30:31], exec, s[4:5]
	v_mul_f32_e32 v77, 0x3fb8aa3b, v94
	v_exp_f32_e32 v77, v77
	s_nop 0
	v_sub_f32_e32 v77, 1.0, v77
	s_andn2_saveexec_b64 s[30:31], s[30:31]
	v_fmamk_f32 v77, v94, 0x3c088889, v174
	v_fmaak_f32 v77, v94, v77, 0x3e2aaaab
	v_fma_f32 v77, v94, v77, 0.5
	v_fma_f32 v77, v94, v77, 1.0
	v_mul_f32_e64 v77, v77, -v94
	s_or_b64 exec, exec, s[30:31]
	v_add_f32_e32 v63, v63, v71
	v_mul_f32_e32 v63, 0xbfb8aa3b, v63
	v_exp_f32_e32 v63, v63
	s_nop 0
	v_add_f32_e32 v63, 1.0, v63
	v_rcp_f32_e32 v94, v63
	v_mul_f32_e32 v63, 0xc1000000, v95
	v_mul_f32_e32 v94, v94, v63
	v_add_f32_e32 v98, v94, v94
	v_cmp_nlt_f32_e32 vcc, s0, v98
	s_and_saveexec_b64 s[4:5], vcc
	s_xor_b64 s[30:31], exec, s[4:5]
	v_mul_f32_e32 v95, 0x3fb8aa3b, v98
	v_exp_f32_e32 v95, v95
	s_nop 0
	v_sub_f32_e32 v95, 1.0, v95
	s_andn2_saveexec_b64 s[30:31], s[30:31]
	v_fmamk_f32 v95, v98, 0x3c088889, v174
	v_fmaak_f32 v95, v98, v95, 0x3e2aaaab
	v_fma_f32 v95, v98, v95, 0.5
	v_fma_f32 v95, v98, v95, 1.0
	v_mul_f32_e64 v95, v95, -v98
	s_or_b64 exec, exec, s[30:31]
	v_add_f32_e32 v64, v64, v72
	v_mul_f32_e32 v64, 0xbfb8aa3b, v64
	v_exp_f32_e32 v64, v64
	s_nop 0
	v_add_f32_e32 v64, 1.0, v64
	v_rcp_f32_e32 v98, v64
	v_mul_f32_e32 v64, 0xc1000000, v96
	v_mul_f32_e32 v96, v98, v64
	v_add_f32_e32 v99, v96, v96
	v_cmp_nlt_f32_e32 vcc, s0, v99
	s_and_saveexec_b64 s[4:5], vcc
	s_xor_b64 s[30:31], exec, s[4:5]
	v_mul_f32_e32 v98, 0x3fb8aa3b, v99
	v_exp_f32_e32 v98, v98
	s_nop 0
	v_sub_f32_e32 v98, 1.0, v98
	s_andn2_saveexec_b64 s[30:31], s[30:31]
	v_fmamk_f32 v98, v99, 0x3c088889, v174
	v_fmaak_f32 v98, v99, v98, 0x3e2aaaab
	v_fma_f32 v98, v99, v98, 0.5
	v_fma_f32 v98, v99, v98, 1.0
	v_mul_f32_e64 v98, v98, -v99
	s_or_b64 exec, exec, s[30:31]
	v_add_f32_e32 v65, v65, v73
	v_mul_f32_e32 v65, 0xbfb8aa3b, v65
	v_exp_f32_e32 v65, v65
	s_nop 0
	v_add_f32_e32 v65, 1.0, v65
	v_rcp_f32_e32 v99, v65
	v_mul_f32_e32 v65, 0xc1000000, v97
	v_mul_f32_e32 v97, v99, v65
	v_add_f32_e32 v100, v97, v97
	v_cmp_nlt_f32_e32 vcc, s0, v100
	s_and_saveexec_b64 s[4:5], vcc
	s_xor_b64 s[30:31], exec, s[4:5]
	v_mul_f32_e32 v99, 0x3fb8aa3b, v100
	v_exp_f32_e32 v99, v99
	s_nop 0
	v_sub_f32_e32 v99, 1.0, v99
	s_andn2_saveexec_b64 s[30:31], s[30:31]
	v_fmamk_f32 v99, v100, 0x3c088889, v174
	v_fmaak_f32 v99, v100, v99, 0x3e2aaaab
	v_fma_f32 v99, v100, v99, 0.5
	v_fma_f32 v99, v100, v99, 1.0
	v_mul_f32_e64 v99, v99, -v100
	s_or_b64 exec, exec, s[30:31]
	v_add_f32_e32 v58, v58, v66
	v_mul_f32_e32 v58, 0xbfb8aa3b, v58
	v_exp_f32_e32 v100, v58
	v_add_f32_e32 v59, v59, v67
	v_mul_f32_e32 v58, 0x3fb8aa3b, v76
	v_sqrt_f32_e32 v77, v77
	v_add_f32_e32 v76, 1.0, v100
	v_mul_f32_e32 v59, 0xbfb8aa3b, v59
	v_rcp_f32_e32 v76, v76
	v_exp_f32_e32 v59, v59
	v_cndmask_b32_e64 v77, v77, 1.0, s[2:3]
	v_add_f32_e32 v60, v60, v68
	s_waitcnt vmcnt(7)
	v_lshlrev_b32_e32 v101, 16, v74
	v_mul_f32_e32 v76, v76, v77
	v_add_f32_e32 v59, 1.0, v59
	v_sqrt_f32_e32 v77, v95
	v_mul_f32_e32 v60, 0xbfb8aa3b, v60
	v_mul_f32_e32 v136, v76, v101
	v_rcp_f32_e32 v76, v59
	v_exp_f32_e32 v60, v60
	v_cndmask_b32_e64 v77, v77, 1.0, s[2:3]
	v_and_b32_e32 v74, 0xffff0000, v74
	v_mul_f32_e32 v76, v76, v77
	v_add_f32_e32 v60, 1.0, v60
	v_sqrt_f32_e32 v77, v98
	v_add_f32_e32 v61, v61, v69
	v_mul_f32_e32 v137, v76, v74
	v_rcp_f32_e32 v74, v60
	v_mul_f32_e32 v61, 0xbfb8aa3b, v61
	v_exp_f32_e32 v61, v61
	v_cndmask_b32_e64 v77, v77, 1.0, s[2:3]
	v_lshlrev_b32_e32 v76, 16, v75
	v_mul_f32_e32 v74, v74, v77
	v_mul_f32_e32 v138, v74, v76
	v_add_f32_e32 v61, 1.0, v61
	v_sqrt_f32_e32 v76, v99
	v_mul_f32_e32 v59, 0x3fb8aa3b, v94
	v_mul_f32_e32 v60, 0x3fb8aa3b, v96
	v_rcp_f32_e32 v74, v61
	v_mul_f32_e32 v61, 0x3fb8aa3b, v97
	v_exp_f32_e32 v58, v58
	v_exp_f32_e32 v59, v59
	v_exp_f32_e32 v60, v60
	v_exp_f32_e32 v61, v61
	v_cndmask_b32_e64 v76, v76, 1.0, s[2:3]
	v_and_b32_e32 v75, 0xffff0000, v75
	v_mul_f32_e32 v74, v74, v76
	v_mul_f32_e32 v139, v74, v75
	global_store_dwordx4 v[130:131], v[58:61], off offset:64
	global_store_dwordx4 v[132:133], v[136:139], off offset:64
	s_waitcnt vmcnt(8)
	s_nop 1
	v_mov_b32_e32 v58, v242
	v_mov_b32_e32 v59, v243
	v_add_f32_e32 v54, v54, v70
	v_mul_f32_e32 v54, 0xbfb8aa3b, v54
	v_exp_f32_e32 v54, v54
	s_nop 0
	v_add_f32_e32 v54, 1.0, v54
	v_rcp_f32_e32 v54, v54
	s_nop 0
	v_mul_f32_e32 v54, v54, v62
	v_add_f32_e32 v61, v54, v54
	v_cmp_nlt_f32_e32 vcc, s0, v61
	s_and_saveexec_b64 s[2:3], vcc
	s_xor_b64 s[2:3], exec, s[2:3]
	v_mul_f32_e32 v60, 0x3fb8aa3b, v61
	v_exp_f32_e32 v60, v60
	s_nop 0
	v_sub_f32_e32 v60, 1.0, v60
	s_andn2_saveexec_b64 s[2:3], s[2:3]
	v_fmamk_f32 v60, v61, 0x3c088889, v174
	v_fmaak_f32 v60, v61, v60, 0x3e2aaaab
	v_fma_f32 v60, v61, v60, 0.5
	v_fma_f32 v60, v61, v60, 1.0
	v_mul_f32_e64 v60, v60, -v61
	s_or_b64 exec, exec, s[2:3]
	v_add_f32_e32 v55, v55, v71
	v_mul_f32_e32 v55, 0xbfb8aa3b, v55
	v_exp_f32_e32 v55, v55
	s_nop 0
	v_add_f32_e32 v55, 1.0, v55
	v_rcp_f32_e32 v55, v55
	s_nop 0
	v_mul_f32_e32 v55, v55, v63
	v_add_f32_e32 v74, v55, v55
	v_cmp_nlt_f32_e32 vcc, s0, v74
	s_and_saveexec_b64 s[2:3], vcc
	s_xor_b64 s[2:3], exec, s[2:3]
	v_mul_f32_e32 v61, 0x3fb8aa3b, v74
	v_exp_f32_e32 v61, v61
	s_nop 0
	v_sub_f32_e32 v61, 1.0, v61
	s_andn2_saveexec_b64 s[2:3], s[2:3]
	v_fmamk_f32 v61, v74, 0x3c088889, v174
	v_fmaak_f32 v61, v74, v61, 0x3e2aaaab
	v_fma_f32 v61, v74, v61, 0.5
	v_fma_f32 v61, v74, v61, 1.0
	v_mul_f32_e64 v61, v61, -v74
	s_or_b64 exec, exec, s[2:3]
	v_add_f32_e32 v56, v56, v72
	v_mul_f32_e32 v56, 0xbfb8aa3b, v56
	v_exp_f32_e32 v56, v56
	s_nop 0
	v_add_f32_e32 v56, 1.0, v56
	v_rcp_f32_e32 v56, v56
	s_nop 0
	v_mul_f32_e32 v56, v56, v64
	v_add_f32_e32 v75, v56, v56
	v_cmp_nlt_f32_e32 vcc, s0, v75
	s_and_saveexec_b64 s[2:3], vcc
	s_xor_b64 s[2:3], exec, s[2:3]
	v_mul_f32_e32 v74, 0x3fb8aa3b, v75
	v_exp_f32_e32 v74, v74
	s_nop 0
	v_sub_f32_e32 v74, 1.0, v74
	s_andn2_saveexec_b64 s[2:3], s[2:3]
	v_fmamk_f32 v74, v75, 0x3c088889, v174
	v_fmaak_f32 v74, v75, v74, 0x3e2aaaab
	v_fma_f32 v74, v75, v74, 0.5
	v_fma_f32 v74, v75, v74, 1.0
	v_mul_f32_e64 v74, v74, -v75
	s_or_b64 exec, exec, s[2:3]
	v_add_f32_e32 v57, v57, v73
	v_mul_f32_e32 v57, 0xbfb8aa3b, v57
	v_exp_f32_e32 v57, v57
	s_nop 0
	v_add_f32_e32 v57, 1.0, v57
	v_rcp_f32_e32 v57, v57
	s_nop 0
	v_mul_f32_e32 v57, v57, v65
	v_add_f32_e32 v76, v57, v57
	v_cmp_nlt_f32_e32 vcc, s0, v76
	s_and_saveexec_b64 s[2:3], vcc
	s_xor_b64 s[2:3], exec, s[2:3]
	v_mul_f32_e32 v75, 0x3fb8aa3b, v76
	v_exp_f32_e32 v75, v75
	s_nop 0
	v_sub_f32_e32 v75, 1.0, v75
	s_andn2_saveexec_b64 s[2:3], s[2:3]
	v_fmamk_f32 v75, v76, 0x3c088889, v174
	v_fmaak_f32 v75, v76, v75, 0x3e2aaaab
	v_fma_f32 v75, v76, v75, 0.5
	v_fma_f32 v75, v76, v75, 1.0
	v_mul_f32_e64 v75, v75, -v76
	s_or_b64 exec, exec, s[2:3]
	v_add_f32_e32 v50, v50, v66
	v_mul_f32_e32 v50, 0xbfb8aa3b, v50
	v_exp_f32_e32 v50, v50
	v_sqrt_f32_e32 v60, v60
	v_add_f32_e32 v52, v52, v68
	v_mul_f32_e32 v54, 0x3fb8aa3b, v54
	v_add_f32_e32 v50, 1.0, v50
	v_rcp_f32_e32 v77, v50
	v_add_f32_e32 v50, v51, v67
	v_mul_f32_e32 v50, 0xbfb8aa3b, v50
	v_exp_f32_e32 v51, v50
	v_mul_f32_e32 v52, 0xbfb8aa3b, v52
	v_exp_f32_e32 v50, v54
	v_mul_f32_e32 v54, v77, v60
	v_add_f32_e32 v51, 1.0, v51
	v_rcp_f32_e32 v60, v51
	v_mul_f32_e32 v51, 0x3fb8aa3b, v55
	v_sqrt_f32_e32 v55, v61
	v_exp_f32_e32 v52, v52
	v_add_f32_e32 v53, v53, v69
	s_nop 0
	v_lshlrev_b32_e32 v76, 16, v58
	v_and_b32_e32 v58, 0xffff0000, v58
	v_mul_f32_e32 v55, v60, v55
	v_add_f32_e32 v52, 1.0, v52
	v_mul_f32_e32 v53, 0xbfb8aa3b, v53
	v_mul_f32_e32 v55, v55, v58
	v_rcp_f32_e32 v58, v52
	v_mul_f32_e32 v52, 0x3fb8aa3b, v56
	v_sqrt_f32_e32 v56, v74
	v_exp_f32_e32 v53, v53
	v_lshlrev_b32_e32 v60, 16, v59
	v_exp_f32_e32 v51, v51
	v_mul_f32_e32 v56, v58, v56
	v_add_f32_e32 v53, 1.0, v53
	v_mul_f32_e32 v56, v56, v60
	v_rcp_f32_e32 v58, v53
	v_sqrt_f32_e32 v60, v75
	v_mul_f32_e32 v53, 0x3fb8aa3b, v57
	v_exp_f32_e32 v52, v52
	v_exp_f32_e32 v53, v53
	v_and_b32_e32 v57, 0xffff0000, v59
	v_mul_f32_e32 v58, v58, v60
	v_mul_f32_e32 v54, v54, v76
	v_mul_f32_e32 v57, v58, v57
	global_store_dwordx4 v[122:123], v[50:53], off offset:64
	global_store_dwordx4 v[124:125], v[54:57], off offset:64
	s_waitcnt vmcnt(9)
	s_nop 1
	v_mov_b32_e32 v50, v244
	v_mov_b32_e32 v51, v245
	v_add_f32_e32 v46, v46, v70
	v_mul_f32_e32 v46, 0xbfb8aa3b, v46
	v_exp_f32_e32 v46, v46
	s_nop 0
	v_add_f32_e32 v46, 1.0, v46
	v_rcp_f32_e32 v46, v46
	s_nop 0
	v_mul_f32_e32 v46, v46, v62
	v_add_f32_e32 v53, v46, v46
	v_cmp_nlt_f32_e32 vcc, s0, v53
	s_and_saveexec_b64 s[2:3], vcc
	s_xor_b64 s[2:3], exec, s[2:3]
	v_mul_f32_e32 v52, 0x3fb8aa3b, v53
	v_exp_f32_e32 v52, v52
	s_nop 0
	v_sub_f32_e32 v52, 1.0, v52
	s_andn2_saveexec_b64 s[2:3], s[2:3]
	v_fmamk_f32 v52, v53, 0x3c088889, v174
	v_fmaak_f32 v52, v53, v52, 0x3e2aaaab
	v_fma_f32 v52, v53, v52, 0.5
	v_fma_f32 v52, v53, v52, 1.0
	v_mul_f32_e64 v52, v52, -v53
	s_or_b64 exec, exec, s[2:3]
	v_add_f32_e32 v47, v47, v71
	v_mul_f32_e32 v47, 0xbfb8aa3b, v47
	v_exp_f32_e32 v47, v47
	s_nop 0
	v_add_f32_e32 v47, 1.0, v47
	v_rcp_f32_e32 v47, v47
	s_nop 0
	v_mul_f32_e32 v47, v47, v63
	v_add_f32_e32 v54, v47, v47
	v_cmp_nlt_f32_e32 vcc, s0, v54
	s_and_saveexec_b64 s[2:3], vcc
	s_xor_b64 s[2:3], exec, s[2:3]
	v_mul_f32_e32 v53, 0x3fb8aa3b, v54
	v_exp_f32_e32 v53, v53
	s_nop 0
	v_sub_f32_e32 v53, 1.0, v53
	s_andn2_saveexec_b64 s[2:3], s[2:3]
	v_fmamk_f32 v53, v54, 0x3c088889, v174
	v_fmaak_f32 v53, v54, v53, 0x3e2aaaab
	v_fma_f32 v53, v54, v53, 0.5
	v_fma_f32 v53, v54, v53, 1.0
	v_mul_f32_e64 v53, v53, -v54
	s_or_b64 exec, exec, s[2:3]
	v_add_f32_e32 v48, v48, v72
	v_mul_f32_e32 v48, 0xbfb8aa3b, v48
	v_exp_f32_e32 v48, v48
	s_nop 0
	v_add_f32_e32 v48, 1.0, v48
	v_rcp_f32_e32 v48, v48
	s_nop 0
	v_mul_f32_e32 v48, v48, v64
	v_add_f32_e32 v55, v48, v48
	v_cmp_nlt_f32_e32 vcc, s0, v55
	s_and_saveexec_b64 s[2:3], vcc
	s_xor_b64 s[2:3], exec, s[2:3]
	v_mul_f32_e32 v54, 0x3fb8aa3b, v55
	v_exp_f32_e32 v54, v54
	s_nop 0
	v_sub_f32_e32 v54, 1.0, v54
	s_andn2_saveexec_b64 s[2:3], s[2:3]
	v_fmamk_f32 v54, v55, 0x3c088889, v174
	v_fmaak_f32 v54, v55, v54, 0x3e2aaaab
	v_fma_f32 v54, v55, v54, 0.5
	v_fma_f32 v54, v55, v54, 1.0
	v_mul_f32_e64 v54, v54, -v55
	s_or_b64 exec, exec, s[2:3]
	v_add_f32_e32 v49, v49, v73
	v_mul_f32_e32 v49, 0xbfb8aa3b, v49
	v_exp_f32_e32 v49, v49
	s_nop 0
	v_add_f32_e32 v49, 1.0, v49
	v_rcp_f32_e32 v49, v49
	s_nop 0
	v_mul_f32_e32 v49, v49, v65
	v_add_f32_e32 v56, v49, v49
	v_cmp_nlt_f32_e32 vcc, s0, v56
	s_and_saveexec_b64 s[2:3], vcc
	s_xor_b64 s[2:3], exec, s[2:3]
	v_mul_f32_e32 v55, 0x3fb8aa3b, v56
	v_exp_f32_e32 v55, v55
	s_nop 0
	v_sub_f32_e32 v55, 1.0, v55
	s_andn2_saveexec_b64 s[2:3], s[2:3]
	v_fmamk_f32 v55, v56, 0x3c088889, v174
	v_fmaak_f32 v55, v56, v55, 0x3e2aaaab
	v_fma_f32 v55, v56, v55, 0.5
	v_fma_f32 v55, v56, v55, 1.0
	v_mul_f32_e64 v55, v55, -v56
	s_or_b64 exec, exec, s[2:3]
	v_add_f32_e32 v42, v42, v66
	v_mul_f32_e32 v42, 0xbfb8aa3b, v42
	v_exp_f32_e32 v42, v42
	v_sqrt_f32_e32 v52, v52
	v_add_f32_e32 v44, v44, v68
	v_mul_f32_e32 v46, 0x3fb8aa3b, v46
	v_add_f32_e32 v42, 1.0, v42
	v_rcp_f32_e32 v57, v42
	v_add_f32_e32 v42, v43, v67
	v_mul_f32_e32 v42, 0xbfb8aa3b, v42
	v_exp_f32_e32 v43, v42
	v_mul_f32_e32 v44, 0xbfb8aa3b, v44
	v_exp_f32_e32 v42, v46
	v_mul_f32_e32 v46, v57, v52
	v_add_f32_e32 v43, 1.0, v43
	v_rcp_f32_e32 v52, v43
	v_mul_f32_e32 v43, 0x3fb8aa3b, v47
	v_sqrt_f32_e32 v47, v53
	v_exp_f32_e32 v44, v44
	v_add_f32_e32 v45, v45, v69
	s_nop 0
	v_lshlrev_b32_e32 v56, 16, v50
	v_and_b32_e32 v50, 0xffff0000, v50
	v_mul_f32_e32 v47, v52, v47
	v_add_f32_e32 v44, 1.0, v44
	v_mul_f32_e32 v45, 0xbfb8aa3b, v45
	v_mul_f32_e32 v47, v47, v50
	v_rcp_f32_e32 v50, v44
	v_mul_f32_e32 v44, 0x3fb8aa3b, v48
	v_sqrt_f32_e32 v48, v54
	v_exp_f32_e32 v45, v45
	v_lshlrev_b32_e32 v52, 16, v51
	v_exp_f32_e32 v43, v43
	v_mul_f32_e32 v48, v50, v48
	v_add_f32_e32 v45, 1.0, v45
	v_mul_f32_e32 v48, v48, v52
	v_rcp_f32_e32 v50, v45
	v_sqrt_f32_e32 v52, v55
	v_mul_f32_e32 v45, 0x3fb8aa3b, v49
	v_exp_f32_e32 v44, v44
	v_exp_f32_e32 v45, v45
	v_and_b32_e32 v49, 0xffff0000, v51
	v_mul_f32_e32 v50, v50, v52
	v_mul_f32_e32 v46, v46, v56
	v_mul_f32_e32 v49, v50, v49
	global_store_dwordx4 v[114:115], v[42:45], off offset:64
	global_store_dwordx4 v[116:117], v[46:49], off offset:64
	s_waitcnt vmcnt(10)
	s_nop 1
	v_mov_b32_e32 v42, v246
	v_mov_b32_e32 v43, v247
	v_add_f32_e32 v38, v38, v70
	v_mul_f32_e32 v38, 0xbfb8aa3b, v38
	v_exp_f32_e32 v38, v38
	s_nop 0
	v_add_f32_e32 v38, 1.0, v38
	v_rcp_f32_e32 v38, v38
	s_nop 0
	v_mul_f32_e32 v38, v38, v62
	v_add_f32_e32 v45, v38, v38
	v_cmp_nlt_f32_e32 vcc, s0, v45
	s_and_saveexec_b64 s[2:3], vcc
	s_xor_b64 s[2:3], exec, s[2:3]
	v_mul_f32_e32 v44, 0x3fb8aa3b, v45
	v_exp_f32_e32 v44, v44
	s_nop 0
	v_sub_f32_e32 v44, 1.0, v44
	s_andn2_saveexec_b64 s[2:3], s[2:3]
	v_fmamk_f32 v44, v45, 0x3c088889, v174
	v_fmaak_f32 v44, v45, v44, 0x3e2aaaab
	v_fma_f32 v44, v45, v44, 0.5
	v_fma_f32 v44, v45, v44, 1.0
	v_mul_f32_e64 v44, v44, -v45
	s_or_b64 exec, exec, s[2:3]
	v_add_f32_e32 v39, v39, v71
	v_mul_f32_e32 v39, 0xbfb8aa3b, v39
	v_exp_f32_e32 v39, v39
	s_nop 0
	v_add_f32_e32 v39, 1.0, v39
	v_rcp_f32_e32 v39, v39
	s_nop 0
	v_mul_f32_e32 v39, v39, v63
	v_add_f32_e32 v46, v39, v39
	v_cmp_nlt_f32_e32 vcc, s0, v46
	s_and_saveexec_b64 s[2:3], vcc
	s_xor_b64 s[2:3], exec, s[2:3]
	v_mul_f32_e32 v45, 0x3fb8aa3b, v46
	v_exp_f32_e32 v45, v45
	s_nop 0
	v_sub_f32_e32 v45, 1.0, v45
	s_andn2_saveexec_b64 s[2:3], s[2:3]
	v_fmamk_f32 v45, v46, 0x3c088889, v174
	v_fmaak_f32 v45, v46, v45, 0x3e2aaaab
	v_fma_f32 v45, v46, v45, 0.5
	v_fma_f32 v45, v46, v45, 1.0
	v_mul_f32_e64 v45, v45, -v46
	s_or_b64 exec, exec, s[2:3]
	v_add_f32_e32 v40, v40, v72
	v_mul_f32_e32 v40, 0xbfb8aa3b, v40
	v_exp_f32_e32 v40, v40
	s_nop 0
	v_add_f32_e32 v40, 1.0, v40
	v_rcp_f32_e32 v40, v40
	s_nop 0
	v_mul_f32_e32 v40, v40, v64
	v_add_f32_e32 v47, v40, v40
	v_cmp_nlt_f32_e32 vcc, s0, v47
	s_and_saveexec_b64 s[2:3], vcc
	s_xor_b64 s[2:3], exec, s[2:3]
	v_mul_f32_e32 v46, 0x3fb8aa3b, v47
	v_exp_f32_e32 v46, v46
	s_nop 0
	v_sub_f32_e32 v46, 1.0, v46
	s_andn2_saveexec_b64 s[2:3], s[2:3]
	v_fmamk_f32 v46, v47, 0x3c088889, v174
	v_fmaak_f32 v46, v47, v46, 0x3e2aaaab
	v_fma_f32 v46, v47, v46, 0.5
	v_fma_f32 v46, v47, v46, 1.0
	v_mul_f32_e64 v46, v46, -v47
	s_or_b64 exec, exec, s[2:3]
	v_add_f32_e32 v41, v41, v73
	v_mul_f32_e32 v41, 0xbfb8aa3b, v41
	v_exp_f32_e32 v41, v41
	s_nop 0
	v_add_f32_e32 v41, 1.0, v41
	v_rcp_f32_e32 v41, v41
	s_nop 0
	v_mul_f32_e32 v41, v41, v65
	v_add_f32_e32 v48, v41, v41
	v_cmp_nlt_f32_e32 vcc, s0, v48
	s_and_saveexec_b64 s[2:3], vcc
	s_xor_b64 s[2:3], exec, s[2:3]
	v_mul_f32_e32 v47, 0x3fb8aa3b, v48
	v_exp_f32_e32 v47, v47
	s_nop 0
	v_sub_f32_e32 v47, 1.0, v47
	s_andn2_saveexec_b64 s[2:3], s[2:3]
	v_fmamk_f32 v47, v48, 0x3c088889, v174
	v_fmaak_f32 v47, v48, v47, 0x3e2aaaab
	v_fma_f32 v47, v48, v47, 0.5
	v_fma_f32 v47, v48, v47, 1.0
	v_mul_f32_e64 v47, v47, -v48
	s_or_b64 exec, exec, s[2:3]
	v_add_f32_e32 v34, v34, v66
	v_mul_f32_e32 v34, 0xbfb8aa3b, v34
	v_exp_f32_e32 v34, v34
	v_sqrt_f32_e32 v44, v44
	v_add_f32_e32 v36, v36, v68
	v_mul_f32_e32 v38, 0x3fb8aa3b, v38
	v_add_f32_e32 v34, 1.0, v34
	v_rcp_f32_e32 v49, v34
	v_add_f32_e32 v34, v35, v67
	v_mul_f32_e32 v34, 0xbfb8aa3b, v34
	v_exp_f32_e32 v35, v34
	v_mul_f32_e32 v36, 0xbfb8aa3b, v36
	v_exp_f32_e32 v34, v38
	v_mul_f32_e32 v38, v49, v44
	v_add_f32_e32 v35, 1.0, v35
	v_rcp_f32_e32 v44, v35
	v_mul_f32_e32 v35, 0x3fb8aa3b, v39
	v_sqrt_f32_e32 v39, v45
	v_exp_f32_e32 v36, v36
	v_add_f32_e32 v37, v37, v69
	s_nop 0
	v_lshlrev_b32_e32 v48, 16, v42
	v_and_b32_e32 v42, 0xffff0000, v42
	v_mul_f32_e32 v39, v44, v39
	v_add_f32_e32 v36, 1.0, v36
	v_mul_f32_e32 v37, 0xbfb8aa3b, v37
	v_mul_f32_e32 v39, v39, v42
	v_rcp_f32_e32 v42, v36
	v_mul_f32_e32 v36, 0x3fb8aa3b, v40
	v_sqrt_f32_e32 v40, v46
	v_exp_f32_e32 v37, v37
	v_lshlrev_b32_e32 v44, 16, v43
	v_exp_f32_e32 v35, v35
	v_mul_f32_e32 v40, v42, v40
	v_add_f32_e32 v37, 1.0, v37
	v_mul_f32_e32 v40, v40, v44
	v_rcp_f32_e32 v42, v37
	v_sqrt_f32_e32 v44, v47
	v_mul_f32_e32 v37, 0x3fb8aa3b, v41
	v_exp_f32_e32 v36, v36
	v_exp_f32_e32 v37, v37
	v_and_b32_e32 v41, 0xffff0000, v43
	v_mul_f32_e32 v42, v42, v44
	v_mul_f32_e32 v38, v38, v48
	v_mul_f32_e32 v41, v42, v41
	global_store_dwordx4 v[106:107], v[34:37], off offset:64
	global_store_dwordx4 v[108:109], v[38:41], off offset:64
	s_waitcnt vmcnt(11)
	s_nop 1
	v_mov_b32_e32 v34, v248
	v_mov_b32_e32 v35, v249
	v_add_f32_e32 v30, v30, v70
	v_mul_f32_e32 v30, 0xbfb8aa3b, v30
	v_exp_f32_e32 v30, v30
	s_nop 0
	v_add_f32_e32 v30, 1.0, v30
	v_rcp_f32_e32 v30, v30
	s_nop 0
	v_mul_f32_e32 v30, v30, v62
	v_add_f32_e32 v37, v30, v30
	v_cmp_nlt_f32_e32 vcc, s0, v37
	s_and_saveexec_b64 s[2:3], vcc
	s_xor_b64 s[2:3], exec, s[2:3]
	v_mul_f32_e32 v36, 0x3fb8aa3b, v37
	v_exp_f32_e32 v36, v36
	s_nop 0
	v_sub_f32_e32 v36, 1.0, v36
	s_andn2_saveexec_b64 s[2:3], s[2:3]
	v_fmamk_f32 v36, v37, 0x3c088889, v174
	v_fmaak_f32 v36, v37, v36, 0x3e2aaaab
	v_fma_f32 v36, v37, v36, 0.5
	v_fma_f32 v36, v37, v36, 1.0
	v_mul_f32_e64 v36, v36, -v37
	s_or_b64 exec, exec, s[2:3]
	v_add_f32_e32 v31, v31, v71
	v_mul_f32_e32 v31, 0xbfb8aa3b, v31
	v_exp_f32_e32 v31, v31
	s_nop 0
	v_add_f32_e32 v31, 1.0, v31
	v_rcp_f32_e32 v31, v31
	s_nop 0
	v_mul_f32_e32 v31, v31, v63
	v_add_f32_e32 v38, v31, v31
	v_cmp_nlt_f32_e32 vcc, s0, v38
	s_and_saveexec_b64 s[2:3], vcc
	s_xor_b64 s[2:3], exec, s[2:3]
	v_mul_f32_e32 v37, 0x3fb8aa3b, v38
	v_exp_f32_e32 v37, v37
	s_nop 0
	v_sub_f32_e32 v37, 1.0, v37
	s_andn2_saveexec_b64 s[2:3], s[2:3]
	v_fmamk_f32 v37, v38, 0x3c088889, v174
	v_fmaak_f32 v37, v38, v37, 0x3e2aaaab
	v_fma_f32 v37, v38, v37, 0.5
	v_fma_f32 v37, v38, v37, 1.0
	v_mul_f32_e64 v37, v37, -v38
	s_or_b64 exec, exec, s[2:3]
	v_add_f32_e32 v32, v32, v72
	v_mul_f32_e32 v32, 0xbfb8aa3b, v32
	v_exp_f32_e32 v32, v32
	s_nop 0
	v_add_f32_e32 v32, 1.0, v32
	v_rcp_f32_e32 v32, v32
	s_nop 0
	v_mul_f32_e32 v32, v32, v64
	v_add_f32_e32 v39, v32, v32
	v_cmp_nlt_f32_e32 vcc, s0, v39
	s_and_saveexec_b64 s[2:3], vcc
	s_xor_b64 s[2:3], exec, s[2:3]
	v_mul_f32_e32 v38, 0x3fb8aa3b, v39
	v_exp_f32_e32 v38, v38
	s_nop 0
	v_sub_f32_e32 v38, 1.0, v38
	s_andn2_saveexec_b64 s[2:3], s[2:3]
	v_fmamk_f32 v38, v39, 0x3c088889, v174
	v_fmaak_f32 v38, v39, v38, 0x3e2aaaab
	v_fma_f32 v38, v39, v38, 0.5
	v_fma_f32 v38, v39, v38, 1.0
	v_mul_f32_e64 v38, v38, -v39
	s_or_b64 exec, exec, s[2:3]
	v_add_f32_e32 v33, v33, v73
	v_mul_f32_e32 v33, 0xbfb8aa3b, v33
	v_exp_f32_e32 v33, v33
	s_nop 0
	v_add_f32_e32 v33, 1.0, v33
	v_rcp_f32_e32 v33, v33
	s_nop 0
	v_mul_f32_e32 v33, v33, v65
	v_add_f32_e32 v40, v33, v33
	v_cmp_nlt_f32_e32 vcc, s0, v40
	s_and_saveexec_b64 s[2:3], vcc
	s_xor_b64 s[2:3], exec, s[2:3]
	v_mul_f32_e32 v39, 0x3fb8aa3b, v40
	v_exp_f32_e32 v39, v39
	s_nop 0
	v_sub_f32_e32 v39, 1.0, v39
	s_andn2_saveexec_b64 s[2:3], s[2:3]
	v_fmamk_f32 v39, v40, 0x3c088889, v174
	v_fmaak_f32 v39, v40, v39, 0x3e2aaaab
	v_fma_f32 v39, v40, v39, 0.5
	v_fma_f32 v39, v40, v39, 1.0
	v_mul_f32_e64 v39, v39, -v40
	s_or_b64 exec, exec, s[2:3]
	v_add_f32_e32 v26, v26, v66
	v_mul_f32_e32 v26, 0xbfb8aa3b, v26
	v_exp_f32_e32 v40, v26
	v_add_f32_e32 v27, v27, v67
	v_mul_f32_e32 v27, 0xbfb8aa3b, v27
	v_mul_f32_e32 v26, 0x3fb8aa3b, v30
	v_add_f32_e32 v30, 1.0, v40
	v_sqrt_f32_e32 v36, v36
	v_exp_f32_e32 v27, v27
	v_rcp_f32_e32 v30, v30
	v_add_f32_e32 v28, v28, v68
	v_cndmask_b32_e64 v36, v36, 1.0, s[8:9]
	v_add_f32_e32 v27, 1.0, v27
	s_nop 0
	v_lshlrev_b32_e32 v41, 16, v34
	v_mul_f32_e32 v30, v30, v36
	v_rcp_f32_e32 v36, v27
	v_mul_f32_e32 v27, 0x3fb8aa3b, v31
	v_and_b32_e32 v31, 0xffff0000, v34
	v_sqrt_f32_e32 v34, v37
	v_mul_f32_e32 v28, 0xbfb8aa3b, v28
	v_exp_f32_e32 v28, v28
	v_add_f32_e32 v29, v29, v69
	v_cndmask_b32_e64 v34, v34, 1.0, s[8:9]
	v_mul_f32_e32 v34, v36, v34
	v_add_f32_e32 v28, 1.0, v28
	v_sqrt_f32_e32 v36, v38
	v_mul_f32_e32 v29, 0xbfb8aa3b, v29
	v_mul_f32_e32 v31, v34, v31
	v_rcp_f32_e32 v34, v28
	v_exp_f32_e32 v29, v29
	v_cndmask_b32_e64 v36, v36, 1.0, s[8:9]
	v_mul_f32_e32 v28, 0x3fb8aa3b, v32
	v_lshlrev_b32_e32 v32, 16, v35
	v_mul_f32_e32 v34, v34, v36
	v_add_f32_e32 v29, 1.0, v29
	v_sqrt_f32_e32 v36, v39
	v_mul_f32_e32 v32, v34, v32
	v_rcp_f32_e32 v34, v29
	v_mul_f32_e32 v29, 0x3fb8aa3b, v33
	v_exp_f32_e32 v26, v26
	v_exp_f32_e32 v27, v27
	v_exp_f32_e32 v28, v28
	v_exp_f32_e32 v29, v29
	v_and_b32_e32 v33, 0xffff0000, v35
	v_cndmask_b32_e64 v35, v36, 1.0, s[8:9]
	v_mul_f32_e32 v34, v34, v35
	v_mul_f32_e32 v30, v30, v41
	v_mul_f32_e32 v33, v34, v33
	global_store_dwordx4 v[90:91], v[26:29], off offset:64
	global_store_dwordx4 v[92:93], v[30:33], off offset:64
	s_waitcnt vmcnt(12)
	s_nop 1
	v_mov_b32_e32 v26, v250
	v_mov_b32_e32 v27, v251
	v_add_f32_e32 v22, v22, v70
	v_mul_f32_e32 v22, 0xbfb8aa3b, v22
	v_exp_f32_e32 v22, v22
	s_nop 0
	v_add_f32_e32 v22, 1.0, v22
	v_rcp_f32_e32 v22, v22
	s_nop 0
	v_mul_f32_e32 v22, v22, v62
	v_add_f32_e32 v29, v22, v22
	v_cmp_nlt_f32_e32 vcc, s0, v29
	s_and_saveexec_b64 s[2:3], vcc
	s_xor_b64 s[2:3], exec, s[2:3]
	v_mul_f32_e32 v28, 0x3fb8aa3b, v29
	v_exp_f32_e32 v28, v28
	s_nop 0
	v_sub_f32_e32 v28, 1.0, v28
	s_andn2_saveexec_b64 s[2:3], s[2:3]
	v_fmamk_f32 v28, v29, 0x3c088889, v174
	v_fmaak_f32 v28, v29, v28, 0x3e2aaaab
	v_fma_f32 v28, v29, v28, 0.5
	v_fma_f32 v28, v29, v28, 1.0
	v_mul_f32_e64 v28, v28, -v29
	s_or_b64 exec, exec, s[2:3]
	v_add_f32_e32 v23, v23, v71
	v_mul_f32_e32 v23, 0xbfb8aa3b, v23
	v_exp_f32_e32 v23, v23
	s_nop 0
	v_add_f32_e32 v23, 1.0, v23
	v_rcp_f32_e32 v23, v23
	s_nop 0
	v_mul_f32_e32 v23, v23, v63
	v_add_f32_e32 v30, v23, v23
	v_cmp_nlt_f32_e32 vcc, s0, v30
	s_and_saveexec_b64 s[2:3], vcc
	s_xor_b64 s[2:3], exec, s[2:3]
	v_mul_f32_e32 v29, 0x3fb8aa3b, v30
	v_exp_f32_e32 v29, v29
	s_nop 0
	v_sub_f32_e32 v29, 1.0, v29
	s_andn2_saveexec_b64 s[2:3], s[2:3]
	v_fmamk_f32 v29, v30, 0x3c088889, v174
	v_fmaak_f32 v29, v30, v29, 0x3e2aaaab
	v_fma_f32 v29, v30, v29, 0.5
	v_fma_f32 v29, v30, v29, 1.0
	v_mul_f32_e64 v29, v29, -v30
	s_or_b64 exec, exec, s[2:3]
	v_add_f32_e32 v24, v24, v72
	v_mul_f32_e32 v24, 0xbfb8aa3b, v24
	v_exp_f32_e32 v24, v24
	s_nop 0
	v_add_f32_e32 v24, 1.0, v24
	v_rcp_f32_e32 v24, v24
	s_nop 0
	v_mul_f32_e32 v24, v24, v64
	v_add_f32_e32 v31, v24, v24
	v_cmp_nlt_f32_e32 vcc, s0, v31
	s_and_saveexec_b64 s[2:3], vcc
	s_xor_b64 s[2:3], exec, s[2:3]
	v_mul_f32_e32 v30, 0x3fb8aa3b, v31
	v_exp_f32_e32 v30, v30
	s_nop 0
	v_sub_f32_e32 v30, 1.0, v30
	s_andn2_saveexec_b64 s[2:3], s[2:3]
	v_fmamk_f32 v30, v31, 0x3c088889, v174
	v_fmaak_f32 v30, v31, v30, 0x3e2aaaab
	v_fma_f32 v30, v31, v30, 0.5
	v_fma_f32 v30, v31, v30, 1.0
	v_mul_f32_e64 v30, v30, -v31
	s_or_b64 exec, exec, s[2:3]
	v_add_f32_e32 v25, v25, v73
	v_mul_f32_e32 v25, 0xbfb8aa3b, v25
	v_exp_f32_e32 v25, v25
	s_nop 0
	v_add_f32_e32 v25, 1.0, v25
	v_rcp_f32_e32 v25, v25
	s_nop 0
	v_mul_f32_e32 v25, v25, v65
	v_add_f32_e32 v32, v25, v25
	v_cmp_nlt_f32_e32 vcc, s0, v32
	s_and_saveexec_b64 s[2:3], vcc
	s_xor_b64 s[2:3], exec, s[2:3]
	v_mul_f32_e32 v31, 0x3fb8aa3b, v32
	v_exp_f32_e32 v31, v31
	s_nop 0
	v_sub_f32_e32 v31, 1.0, v31
	s_andn2_saveexec_b64 s[2:3], s[2:3]
	v_fmamk_f32 v31, v32, 0x3c088889, v174
	v_fmaak_f32 v31, v32, v31, 0x3e2aaaab
	v_fma_f32 v31, v32, v31, 0.5
	v_fma_f32 v31, v32, v31, 1.0
	v_mul_f32_e64 v31, v31, -v32
	s_or_b64 exec, exec, s[2:3]
	v_add_f32_e32 v18, v18, v66
	v_mul_f32_e32 v18, 0xbfb8aa3b, v18
	v_exp_f32_e32 v18, v18
	v_sqrt_f32_e32 v28, v28
	v_add_f32_e32 v20, v20, v68
	v_mul_f32_e32 v22, 0x3fb8aa3b, v22
	v_add_f32_e32 v18, 1.0, v18
	v_rcp_f32_e32 v33, v18
	v_add_f32_e32 v18, v19, v67
	v_mul_f32_e32 v18, 0xbfb8aa3b, v18
	v_exp_f32_e32 v19, v18
	v_mul_f32_e32 v20, 0xbfb8aa3b, v20
	v_exp_f32_e32 v18, v22
	v_mul_f32_e32 v22, v33, v28
	v_add_f32_e32 v19, 1.0, v19
	v_rcp_f32_e32 v28, v19
	v_mul_f32_e32 v19, 0x3fb8aa3b, v23
	v_sqrt_f32_e32 v23, v29
	v_exp_f32_e32 v20, v20
	v_add_f32_e32 v21, v21, v69
	s_nop 0
	v_lshlrev_b32_e32 v32, 16, v26
	v_and_b32_e32 v26, 0xffff0000, v26
	v_mul_f32_e32 v23, v28, v23
	v_add_f32_e32 v20, 1.0, v20
	v_mul_f32_e32 v21, 0xbfb8aa3b, v21
	v_mul_f32_e32 v23, v23, v26
	v_rcp_f32_e32 v26, v20
	v_mul_f32_e32 v20, 0x3fb8aa3b, v24
	v_sqrt_f32_e32 v24, v30
	v_exp_f32_e32 v21, v21
	v_lshlrev_b32_e32 v28, 16, v27
	v_exp_f32_e32 v19, v19
	v_mul_f32_e32 v24, v26, v24
	v_add_f32_e32 v21, 1.0, v21
	v_mul_f32_e32 v24, v24, v28
	v_rcp_f32_e32 v26, v21
	v_sqrt_f32_e32 v28, v31
	v_mul_f32_e32 v21, 0x3fb8aa3b, v25
	v_exp_f32_e32 v20, v20
	v_exp_f32_e32 v21, v21
	v_and_b32_e32 v25, 0xffff0000, v27
	v_mul_f32_e32 v26, v26, v28
	v_mul_f32_e32 v22, v22, v32
	v_mul_f32_e32 v25, v26, v25
	global_store_dwordx4 v[82:83], v[18:21], off offset:64
	global_store_dwordx4 v[84:85], v[22:25], off offset:64
	s_waitcnt vmcnt(13)
	s_nop 1
	v_mov_b32_e32 v18, v180
	v_mov_b32_e32 v19, v181
	v_add_f32_e32 v14, v14, v70
	v_mul_f32_e32 v14, 0xbfb8aa3b, v14
	v_exp_f32_e32 v14, v14
	s_nop 0
	v_add_f32_e32 v14, 1.0, v14
	v_rcp_f32_e32 v14, v14
	s_nop 0
	v_mul_f32_e32 v14, v14, v62
	v_add_f32_e32 v21, v14, v14
	v_cmp_nlt_f32_e32 vcc, s0, v21
	s_and_saveexec_b64 s[2:3], vcc
	s_xor_b64 s[2:3], exec, s[2:3]
	v_mul_f32_e32 v20, 0x3fb8aa3b, v21
	v_exp_f32_e32 v20, v20
	s_nop 0
	v_sub_f32_e32 v20, 1.0, v20
	s_andn2_saveexec_b64 s[2:3], s[2:3]
	v_fmamk_f32 v20, v21, 0x3c088889, v174
	v_fmaak_f32 v20, v21, v20, 0x3e2aaaab
	v_fma_f32 v20, v21, v20, 0.5
	v_fma_f32 v20, v21, v20, 1.0
	v_mul_f32_e64 v20, v20, -v21
	s_or_b64 exec, exec, s[2:3]
	v_add_f32_e32 v15, v15, v71
	v_mul_f32_e32 v15, 0xbfb8aa3b, v15
	v_exp_f32_e32 v15, v15
	s_nop 0
	v_add_f32_e32 v15, 1.0, v15
	v_rcp_f32_e32 v15, v15
	s_nop 0
	v_mul_f32_e32 v15, v15, v63
	v_add_f32_e32 v22, v15, v15
	v_cmp_nlt_f32_e32 vcc, s0, v22
	s_and_saveexec_b64 s[2:3], vcc
	s_xor_b64 s[2:3], exec, s[2:3]
	v_mul_f32_e32 v21, 0x3fb8aa3b, v22
	v_exp_f32_e32 v21, v21
	s_nop 0
	v_sub_f32_e32 v21, 1.0, v21
	s_andn2_saveexec_b64 s[2:3], s[2:3]
	v_fmamk_f32 v21, v22, 0x3c088889, v174
	v_fmaak_f32 v21, v22, v21, 0x3e2aaaab
	v_fma_f32 v21, v22, v21, 0.5
	v_fma_f32 v21, v22, v21, 1.0
	v_mul_f32_e64 v21, v21, -v22
	s_or_b64 exec, exec, s[2:3]
	v_add_f32_e32 v16, v16, v72
	v_mul_f32_e32 v16, 0xbfb8aa3b, v16
	v_exp_f32_e32 v16, v16
	s_nop 0
	v_add_f32_e32 v16, 1.0, v16
	v_rcp_f32_e32 v16, v16
	s_nop 0
	v_mul_f32_e32 v16, v16, v64
	v_add_f32_e32 v23, v16, v16
	v_cmp_nlt_f32_e32 vcc, s0, v23
	s_and_saveexec_b64 s[2:3], vcc
	s_xor_b64 s[2:3], exec, s[2:3]
	v_mul_f32_e32 v22, 0x3fb8aa3b, v23
	v_exp_f32_e32 v22, v22
	s_nop 0
	v_sub_f32_e32 v22, 1.0, v22
	s_andn2_saveexec_b64 s[2:3], s[2:3]
	v_fmamk_f32 v22, v23, 0x3c088889, v174
	v_fmaak_f32 v22, v23, v22, 0x3e2aaaab
	v_fma_f32 v22, v23, v22, 0.5
	v_fma_f32 v22, v23, v22, 1.0
	v_mul_f32_e64 v22, v22, -v23
	s_or_b64 exec, exec, s[2:3]
	v_add_f32_e32 v17, v17, v73
	v_mul_f32_e32 v17, 0xbfb8aa3b, v17
	v_exp_f32_e32 v17, v17
	s_nop 0
	v_add_f32_e32 v17, 1.0, v17
	v_rcp_f32_e32 v17, v17
	s_nop 0
	v_mul_f32_e32 v17, v17, v65
	v_add_f32_e32 v24, v17, v17
	v_cmp_nlt_f32_e32 vcc, s0, v24
	s_and_saveexec_b64 s[2:3], vcc
	s_xor_b64 s[2:3], exec, s[2:3]
	v_mul_f32_e32 v23, 0x3fb8aa3b, v24
	v_exp_f32_e32 v23, v23
	s_nop 0
	v_sub_f32_e32 v23, 1.0, v23
	s_andn2_saveexec_b64 s[2:3], s[2:3]
	v_fmamk_f32 v23, v24, 0x3c088889, v174
	v_fmaak_f32 v23, v24, v23, 0x3e2aaaab
	v_fma_f32 v23, v24, v23, 0.5
	v_fma_f32 v23, v24, v23, 1.0
	v_mul_f32_e64 v23, v23, -v24
	s_or_b64 exec, exec, s[2:3]
	v_add_f32_e32 v10, v10, v66
	v_mul_f32_e32 v10, 0xbfb8aa3b, v10
	v_exp_f32_e32 v10, v10
	v_sqrt_f32_e32 v20, v20
	v_add_f32_e32 v12, v12, v68
	v_mul_f32_e32 v14, 0x3fb8aa3b, v14
	v_add_f32_e32 v10, 1.0, v10
	v_rcp_f32_e32 v25, v10
	v_add_f32_e32 v10, v11, v67
	v_mul_f32_e32 v10, 0xbfb8aa3b, v10
	v_exp_f32_e32 v11, v10
	v_mul_f32_e32 v12, 0xbfb8aa3b, v12
	v_exp_f32_e32 v10, v14
	v_mul_f32_e32 v14, v25, v20
	v_add_f32_e32 v11, 1.0, v11
	v_rcp_f32_e32 v20, v11
	v_mul_f32_e32 v11, 0x3fb8aa3b, v15
	v_sqrt_f32_e32 v15, v21
	v_exp_f32_e32 v12, v12
	v_add_f32_e32 v13, v13, v69
	s_nop 0
	v_lshlrev_b32_e32 v24, 16, v18
	v_and_b32_e32 v18, 0xffff0000, v18
	v_mul_f32_e32 v15, v20, v15
	v_add_f32_e32 v12, 1.0, v12
	v_mul_f32_e32 v13, 0xbfb8aa3b, v13
	v_mul_f32_e32 v15, v15, v18
	v_rcp_f32_e32 v18, v12
	v_mul_f32_e32 v12, 0x3fb8aa3b, v16
	v_sqrt_f32_e32 v16, v22
	v_exp_f32_e32 v13, v13
	v_lshlrev_b32_e32 v20, 16, v19
	v_exp_f32_e32 v11, v11
	v_mul_f32_e32 v16, v18, v16
	v_add_f32_e32 v13, 1.0, v13
	v_mul_f32_e32 v16, v16, v20
	v_rcp_f32_e32 v18, v13
	v_sqrt_f32_e32 v20, v23
	v_mul_f32_e32 v13, 0x3fb8aa3b, v17
	v_exp_f32_e32 v12, v12
	v_exp_f32_e32 v13, v13
	v_and_b32_e32 v17, 0xffff0000, v19
	v_mul_f32_e32 v18, v18, v20
	v_mul_f32_e32 v14, v14, v24
	v_mul_f32_e32 v17, v18, v17
	global_store_dwordx4 v[88:89], v[10:13], off offset:64
	global_store_dwordx4 v[104:105], v[14:17], off offset:64
	s_waitcnt vmcnt(14)
	s_nop 1
	v_mov_b32_e32 v10, v182
	v_mov_b32_e32 v11, v183
	v_add_f32_e32 v6, v6, v70
	v_mul_f32_e32 v6, 0xbfb8aa3b, v6
	v_exp_f32_e32 v6, v6
	s_nop 0
	v_add_f32_e32 v6, 1.0, v6
	v_rcp_f32_e32 v6, v6
	s_nop 0
	v_mul_f32_e32 v13, v6, v62
	v_add_f32_e32 v12, v13, v13
	v_cmp_nlt_f32_e32 vcc, s0, v12
	s_and_saveexec_b64 s[2:3], vcc
	s_xor_b64 s[2:3], exec, s[2:3]
	v_mul_f32_e32 v6, 0x3fb8aa3b, v12
	v_exp_f32_e32 v6, v6
	s_nop 0
	v_sub_f32_e32 v6, 1.0, v6
	s_andn2_saveexec_b64 s[2:3], s[2:3]
	v_fmamk_f32 v6, v12, 0x3c088889, v174
	v_fmaak_f32 v6, v12, v6, 0x3e2aaaab
	v_fma_f32 v6, v12, v6, 0.5
	v_fma_f32 v6, v12, v6, 1.0
	v_mul_f32_e64 v6, v6, -v12
	s_or_b64 exec, exec, s[2:3]
	v_add_f32_e32 v7, v7, v71
	v_mul_f32_e32 v7, 0xbfb8aa3b, v7
	v_exp_f32_e32 v7, v7
	s_nop 0
	v_add_f32_e32 v7, 1.0, v7
	v_rcp_f32_e32 v7, v7
	s_nop 0
	v_mul_f32_e32 v14, v7, v63
	v_add_f32_e32 v7, v14, v14
	v_cmp_nlt_f32_e32 vcc, s0, v7
	s_and_saveexec_b64 s[2:3], vcc
	s_xor_b64 s[2:3], exec, s[2:3]
	v_mul_f32_e32 v7, 0x3fb8aa3b, v7
	v_exp_f32_e32 v7, v7
	s_nop 0
	v_sub_f32_e32 v12, 1.0, v7
	s_andn2_saveexec_b64 s[2:3], s[2:3]
	v_fmamk_f32 v12, v7, 0x3c088889, v174
	v_fmaak_f32 v12, v7, v12, 0x3e2aaaab
	v_fma_f32 v12, v7, v12, 0.5
	v_fma_f32 v12, v7, v12, 1.0
	v_mul_f32_e64 v12, v12, -v7
	s_or_b64 exec, exec, s[2:3]
	v_add_f32_e32 v7, v8, v72
	v_mul_f32_e32 v7, 0xbfb8aa3b, v7
	v_exp_f32_e32 v7, v7
	s_nop 0
	v_add_f32_e32 v7, 1.0, v7
	v_rcp_f32_e32 v7, v7
	s_nop 0
	v_mul_f32_e32 v15, v7, v64
	v_add_f32_e32 v8, v15, v15
	v_cmp_nlt_f32_e32 vcc, s0, v8
	s_and_saveexec_b64 s[2:3], vcc
	s_xor_b64 s[2:3], exec, s[2:3]
	v_mul_f32_e32 v7, 0x3fb8aa3b, v8
	v_exp_f32_e32 v7, v7
	s_nop 0
	v_sub_f32_e32 v7, 1.0, v7
	s_andn2_saveexec_b64 s[2:3], s[2:3]
	v_fmamk_f32 v7, v8, 0x3c088889, v174
	v_fmaak_f32 v7, v8, v7, 0x3e2aaaab
	v_fma_f32 v7, v8, v7, 0.5
	v_fma_f32 v7, v8, v7, 1.0
	v_mul_f32_e64 v7, v7, -v8
	s_or_b64 exec, exec, s[2:3]
	v_add_f32_e32 v8, v9, v73
	v_mul_f32_e32 v8, 0xbfb8aa3b, v8
	v_exp_f32_e32 v8, v8
	s_nop 0
	v_add_f32_e32 v8, 1.0, v8
	v_rcp_f32_e32 v8, v8
	s_nop 0
	v_mul_f32_e32 v9, v8, v65
	v_add_f32_e32 v16, v9, v9
	v_cmp_nlt_f32_e32 vcc, s0, v16
	s_and_saveexec_b64 s[2:3], vcc
	s_xor_b64 s[2:3], exec, s[2:3]
	v_mul_f32_e32 v8, 0x3fb8aa3b, v16
	v_exp_f32_e32 v8, v8
	s_nop 0
	v_sub_f32_e32 v8, 1.0, v8
	s_andn2_saveexec_b64 s[2:3], s[2:3]
	s_cbranch_execz .LBB0_312
	v_fmamk_f32 v8, v16, 0x3c088889, v174
	v_fmaak_f32 v8, v16, v8, 0x3e2aaaab
	v_fma_f32 v8, v16, v8, 0.5
	v_fma_f32 v8, v16, v8, 1.0
	v_mul_f32_e64 v8, v8, -v16
	s_branch .LBB0_312
